# lever 2 (epilogue de-serialisation): LN residual loads of batches 0-2 issued together into three register sets, counted waits 16/8/0
# speedup vs baseline: 1.0097x; 1.0097x over previous
.LBB0_438:
	s_lshl_b32 s2, s14, 5
	s_lshl_b32 s3, s0, 8
	s_or_b32 s2, s3, s2
	v_lshrrev_b32_e32 v0, 2, v148
	s_lshl_b32 s6, s87, 8
	v_and_or_b32 v164, v0, 12, s2
	s_add_i32 s2, s6, s96
	v_or_b32_e32 v0, s2, v176
	v_readlane_b32 s2, v253, 15
	v_lshl_add_u32 v2, v0, 10, v164
	v_readlane_b32 s3, v253, 16
	s_waitcnt vmcnt(0)
	s_barrier
	v_mov_b32_e32 v134, v3
	v_lshl_add_u64 v[0:1], v[2:3], 1, s[2:3]
	global_load_dwordx2 v[132:133], v[0:1], off
	global_load_dwordx2 v[136:137], v[0:1], off offset:32
	global_load_dwordx2 v[140:141], v[0:1], off offset:256
	global_load_dwordx2 v[144:145], v[0:1], off offset:288
	v_add_u32_e32 v0, 0x4000, v2
	v_mov_b32_e32 v1, v3
	v_lshl_add_u64 v[0:1], v[0:1], 1, s[2:3]
	global_load_dwordx2 v[150:151], v[0:1], off
	global_load_dwordx2 v[178:179], v[0:1], off offset:32
	global_load_dwordx2 v[182:183], v[0:1], off offset:256
	global_load_dwordx2 v[186:187], v[0:1], off offset:288
	v_mov_b32_e32 v135, v3
	v_mov_b32_e32 v138, v3
	v_mov_b32_e32 v139, v3
	v_mov_b32_e32 v142, v3
	v_mov_b32_e32 v143, v3
	v_mov_b32_e32 v146, v3
	v_mov_b32_e32 v147, v3
	v_mov_b32_e32 v152, v3
	v_mov_b32_e32 v153, v3
	v_mov_b32_e32 v180, v3
	v_mov_b32_e32 v181, v3
	v_mov_b32_e32 v184, v3
	v_mov_b32_e32 v185, v3
	v_mov_b32_e32 v188, v3
	v_mov_b32_e32 v189, v3
	v_and_b32_e32 v149, 63, v148
	v_add_u32_e32 v0, 0x8000, v2
	v_mov_b32_e32 v1, v3
	v_lshl_add_u64 v[0:1], v[0:1], 1, s[2:3]
	global_load_dwordx2 v[200:201], v[0:1], off
	global_load_dwordx2 v[202:203], v[0:1], off offset:32
	global_load_dwordx2 v[204:205], v[0:1], off offset:256
	global_load_dwordx2 v[206:207], v[0:1], off offset:288
	v_add_u32_e32 v0, 0xc000, v2
	v_mov_b32_e32 v1, v3
	v_lshl_add_u64 v[0:1], v[0:1], 1, s[2:3]
	global_load_dwordx2 v[208:209], v[0:1], off
	global_load_dwordx2 v[210:211], v[0:1], off offset:32
	global_load_dwordx2 v[212:213], v[0:1], off offset:256
	global_load_dwordx2 v[214:215], v[0:1], off offset:288
	v_add_u32_e32 v0, 0x20000, v2
	v_mov_b32_e32 v1, v3
	v_lshl_add_u64 v[0:1], v[0:1], 1, s[2:3]
	global_load_dwordx2 v[222:223], v[0:1], off
	global_load_dwordx2 v[220:221], v[0:1], off offset:32
	global_load_dwordx2 v[218:219], v[0:1], off offset:256
	global_load_dwordx2 v[216:217], v[0:1], off offset:288
	v_add_u32_e32 v0, 0x24000, v2
	v_mov_b32_e32 v1, v3
	v_lshl_add_u64 v[0:1], v[0:1], 1, s[2:3]
	global_load_dwordx2 v[224:225], v[0:1], off
	global_load_dwordx2 v[226:227], v[0:1], off offset:32
	global_load_dwordx2 v[228:229], v[0:1], off offset:256
	global_load_dwordx2 v[230:231], v[0:1], off offset:288
	s_waitcnt vmcnt(16)
	s_nop 0
	v_cvt_f32_f16_e32 v0, v132
	v_cvt_f32_f16_sdwa v1, v132 dst_sel:DWORD dst_unused:UNUSED_PAD src0_sel:WORD_1
	v_cvt_f32_f16_e32 v132, v133
	v_cvt_f32_f16_sdwa v133, v133 dst_sel:DWORD dst_unused:UNUSED_PAD src0_sel:WORD_1
	v_mov_b32_e32 v134, v3
	v_pk_fma_f32 v[28:29], v[0:1], s[86:87], v[28:29] op_sel_hi:[1,0,1]
	v_cvt_f32_f16_e32 v0, v136
	v_pk_fma_f32 v[30:31], v[132:133], s[86:87], v[30:31] op_sel_hi:[1,0,1]
	v_cvt_f32_f16_sdwa v1, v136 dst_sel:DWORD dst_unused:UNUSED_PAD src0_sel:WORD_1
	v_cvt_f32_f16_e32 v132, v137
	v_cvt_f32_f16_sdwa v133, v137 dst_sel:DWORD dst_unused:UNUSED_PAD src0_sel:WORD_1
	v_mov_b32_e32 v135, v3
	v_pk_fma_f32 v[20:21], v[0:1], s[86:87], v[20:21] op_sel_hi:[1,0,1]
	v_cvt_f32_f16_e32 v0, v140
	v_pk_fma_f32 v[22:23], v[132:133], s[86:87], v[22:23] op_sel_hi:[1,0,1]
	v_cvt_f32_f16_sdwa v1, v140 dst_sel:DWORD dst_unused:UNUSED_PAD src0_sel:WORD_1
	v_cvt_f32_f16_e32 v132, v141
	v_cvt_f32_f16_sdwa v133, v141 dst_sel:DWORD dst_unused:UNUSED_PAD src0_sel:WORD_1
	v_mov_b32_e32 v138, v3
	v_pk_fma_f32 v[12:13], v[0:1], s[86:87], v[12:13] op_sel_hi:[1,0,1]
	v_cvt_f32_f16_e32 v0, v144
	v_pk_fma_f32 v[14:15], v[132:133], s[86:87], v[14:15] op_sel_hi:[1,0,1]
	v_cvt_f32_f16_sdwa v1, v144 dst_sel:DWORD dst_unused:UNUSED_PAD src0_sel:WORD_1
	v_cvt_f32_f16_e32 v132, v145
	v_cvt_f32_f16_sdwa v133, v145 dst_sel:DWORD dst_unused:UNUSED_PAD src0_sel:WORD_1
	v_mov_b32_e32 v139, v3
	v_pk_fma_f32 v[4:5], v[0:1], s[86:87], v[4:5] op_sel_hi:[1,0,1]
	v_cvt_f32_f16_e32 v0, v150
	v_pk_fma_f32 v[6:7], v[132:133], s[86:87], v[6:7] op_sel_hi:[1,0,1]
	v_cvt_f32_f16_sdwa v1, v150 dst_sel:DWORD dst_unused:UNUSED_PAD src0_sel:WORD_1
	v_cvt_f32_f16_e32 v132, v151
	v_cvt_f32_f16_sdwa v133, v151 dst_sel:DWORD dst_unused:UNUSED_PAD src0_sel:WORD_1
	v_pk_fma_f32 v[32:33], v[0:1], s[86:87], v[32:33] op_sel_hi:[1,0,1]
	v_cvt_f32_f16_e32 v0, v178
	v_pk_fma_f32 v[34:35], v[132:133], s[86:87], v[34:35] op_sel_hi:[1,0,1]
	v_cvt_f32_f16_sdwa v1, v178 dst_sel:DWORD dst_unused:UNUSED_PAD src0_sel:WORD_1
	v_cvt_f32_f16_e32 v132, v179
	v_cvt_f32_f16_sdwa v133, v179 dst_sel:DWORD dst_unused:UNUSED_PAD src0_sel:WORD_1
	v_mov_b32_e32 v142, v3
	v_pk_fma_f32 v[24:25], v[0:1], s[86:87], v[24:25] op_sel_hi:[1,0,1]
	v_cvt_f32_f16_e32 v0, v182
	v_pk_fma_f32 v[26:27], v[132:133], s[86:87], v[26:27] op_sel_hi:[1,0,1]
	v_cvt_f32_f16_sdwa v1, v182 dst_sel:DWORD dst_unused:UNUSED_PAD src0_sel:WORD_1
	v_cvt_f32_f16_e32 v132, v183
	v_cvt_f32_f16_sdwa v133, v183 dst_sel:DWORD dst_unused:UNUSED_PAD src0_sel:WORD_1
	v_mov_b32_e32 v143, v3
	v_pk_fma_f32 v[16:17], v[0:1], s[86:87], v[16:17] op_sel_hi:[1,0,1]
	v_cvt_f32_f16_e32 v0, v186
	v_pk_fma_f32 v[18:19], v[132:133], s[86:87], v[18:19] op_sel_hi:[1,0,1]
	v_cvt_f32_f16_sdwa v1, v186 dst_sel:DWORD dst_unused:UNUSED_PAD src0_sel:WORD_1
	v_cvt_f32_f16_e32 v132, v187
	v_cvt_f32_f16_sdwa v133, v187 dst_sel:DWORD dst_unused:UNUSED_PAD src0_sel:WORD_1
	v_mov_b32_e32 v146, v3
	v_pk_fma_f32 v[8:9], v[0:1], s[86:87], v[8:9] op_sel_hi:[1,0,1]
	v_pk_fma_f32 v[10:11], v[132:133], s[86:87], v[10:11] op_sel_hi:[1,0,1]
	v_mov_b32_e32 v147, v3
	v_mov_b32_e32 v152, v3
	v_mov_b32_e32 v153, v3
	v_mov_b32_e32 v180, v3
	v_mov_b32_e32 v181, v3
	v_mov_b32_e32 v184, v3
	v_mov_b32_e32 v185, v3
	v_mov_b32_e32 v188, v3
	v_mov_b32_e32 v189, v3
	s_waitcnt vmcnt(8)
	s_nop 0
	v_cvt_f32_f16_e32 v0, v200
	v_cvt_f32_f16_sdwa v1, v200 dst_sel:DWORD dst_unused:UNUSED_PAD src0_sel:WORD_1
	v_cvt_f32_f16_e32 v200, v201
	v_cvt_f32_f16_sdwa v201, v201 dst_sel:DWORD dst_unused:UNUSED_PAD src0_sel:WORD_1
	v_mov_b32_e32 v146, v3
	v_pk_fma_f32 v[60:61], v[0:1], s[86:87], v[60:61] op_sel_hi:[1,0,1]
	v_cvt_f32_f16_e32 v0, v202
	v_pk_fma_f32 v[62:63], v[200:201], s[86:87], v[62:63] op_sel_hi:[1,0,1]
	v_cvt_f32_f16_sdwa v1, v202 dst_sel:DWORD dst_unused:UNUSED_PAD src0_sel:WORD_1
	v_cvt_f32_f16_e32 v200, v203
	v_cvt_f32_f16_sdwa v201, v203 dst_sel:DWORD dst_unused:UNUSED_PAD src0_sel:WORD_1
	v_mov_b32_e32 v147, v3
	v_pk_fma_f32 v[52:53], v[0:1], s[86:87], v[52:53] op_sel_hi:[1,0,1]
	v_cvt_f32_f16_e32 v0, v204
	v_pk_fma_f32 v[54:55], v[200:201], s[86:87], v[54:55] op_sel_hi:[1,0,1]
	v_cvt_f32_f16_sdwa v1, v204 dst_sel:DWORD dst_unused:UNUSED_PAD src0_sel:WORD_1
	v_cvt_f32_f16_e32 v200, v205
	v_cvt_f32_f16_sdwa v201, v205 dst_sel:DWORD dst_unused:UNUSED_PAD src0_sel:WORD_1
	v_mov_b32_e32 v142, v3
	v_pk_fma_f32 v[44:45], v[0:1], s[86:87], v[44:45] op_sel_hi:[1,0,1]
	v_cvt_f32_f16_e32 v0, v206
	v_pk_fma_f32 v[46:47], v[200:201], s[86:87], v[46:47] op_sel_hi:[1,0,1]
	v_cvt_f32_f16_sdwa v1, v206 dst_sel:DWORD dst_unused:UNUSED_PAD src0_sel:WORD_1
	v_cvt_f32_f16_e32 v200, v207
	v_cvt_f32_f16_sdwa v201, v207 dst_sel:DWORD dst_unused:UNUSED_PAD src0_sel:WORD_1
	v_mov_b32_e32 v143, v3
	v_pk_fma_f32 v[36:37], v[0:1], s[86:87], v[36:37] op_sel_hi:[1,0,1]
	v_cvt_f32_f16_e32 v0, v208
	v_pk_fma_f32 v[38:39], v[200:201], s[86:87], v[38:39] op_sel_hi:[1,0,1]
	v_cvt_f32_f16_sdwa v1, v208 dst_sel:DWORD dst_unused:UNUSED_PAD src0_sel:WORD_1
	v_cvt_f32_f16_e32 v200, v209
	v_cvt_f32_f16_sdwa v201, v209 dst_sel:DWORD dst_unused:UNUSED_PAD src0_sel:WORD_1
	v_pk_fma_f32 v[64:65], v[0:1], s[86:87], v[64:65] op_sel_hi:[1,0,1]
	v_cvt_f32_f16_e32 v0, v210
	v_pk_fma_f32 v[66:67], v[200:201], s[86:87], v[66:67] op_sel_hi:[1,0,1]
	v_cvt_f32_f16_sdwa v1, v210 dst_sel:DWORD dst_unused:UNUSED_PAD src0_sel:WORD_1
	v_cvt_f32_f16_e32 v200, v211
	v_cvt_f32_f16_sdwa v201, v211 dst_sel:DWORD dst_unused:UNUSED_PAD src0_sel:WORD_1
	v_mov_b32_e32 v138, v3
	v_pk_fma_f32 v[56:57], v[0:1], s[86:87], v[56:57] op_sel_hi:[1,0,1]
	v_cvt_f32_f16_e32 v0, v212
	v_pk_fma_f32 v[58:59], v[200:201], s[86:87], v[58:59] op_sel_hi:[1,0,1]
	v_cvt_f32_f16_sdwa v1, v212 dst_sel:DWORD dst_unused:UNUSED_PAD src0_sel:WORD_1
	v_cvt_f32_f16_e32 v200, v213
	v_cvt_f32_f16_sdwa v201, v213 dst_sel:DWORD dst_unused:UNUSED_PAD src0_sel:WORD_1
	v_mov_b32_e32 v139, v3
	v_pk_fma_f32 v[48:49], v[0:1], s[86:87], v[48:49] op_sel_hi:[1,0,1]
	v_cvt_f32_f16_e32 v0, v214
	v_pk_fma_f32 v[50:51], v[200:201], s[86:87], v[50:51] op_sel_hi:[1,0,1]
	v_cvt_f32_f16_sdwa v1, v214 dst_sel:DWORD dst_unused:UNUSED_PAD src0_sel:WORD_1
	v_cvt_f32_f16_e32 v200, v215
	v_cvt_f32_f16_sdwa v201, v215 dst_sel:DWORD dst_unused:UNUSED_PAD src0_sel:WORD_1
	v_mov_b32_e32 v134, v3
	v_pk_fma_f32 v[40:41], v[0:1], s[86:87], v[40:41] op_sel_hi:[1,0,1]
	v_pk_fma_f32 v[42:43], v[200:201], s[86:87], v[42:43] op_sel_hi:[1,0,1]
	v_mov_b32_e32 v135, v3
	v_mov_b32_e32 v152, v3
	v_mov_b32_e32 v153, v3
	v_mov_b32_e32 v180, v3
	v_mov_b32_e32 v181, v3
	v_mov_b32_e32 v184, v3
	v_mov_b32_e32 v185, v3
	v_mov_b32_e32 v188, v3
	v_mov_b32_e32 v189, v3
	s_waitcnt vmcnt(0)
	s_nop 0
	v_cvt_f32_f16_e32 v0, v222
	v_cvt_f32_f16_sdwa v1, v222 dst_sel:DWORD dst_unused:UNUSED_PAD src0_sel:WORD_1
	v_cvt_f32_f16_e32 v134, v223
	v_cvt_f32_f16_sdwa v135, v223 dst_sel:DWORD dst_unused:UNUSED_PAD src0_sel:WORD_1
	v_mov_b32_e32 v142, v3
	v_pk_fma_f32 v[92:93], v[0:1], s[86:87], v[92:93] op_sel_hi:[1,0,1]
	v_cvt_f32_f16_e32 v0, v220
	v_cvt_f32_f16_sdwa v1, v220 dst_sel:DWORD dst_unused:UNUSED_PAD src0_sel:WORD_1
	v_pk_fma_f32 v[94:95], v[134:135], s[86:87], v[94:95] op_sel_hi:[1,0,1]
	v_cvt_f32_f16_e32 v134, v221
	v_cvt_f32_f16_sdwa v135, v221 dst_sel:DWORD dst_unused:UNUSED_PAD src0_sel:WORD_1
	v_pk_fma_f32 v[84:85], v[0:1], s[86:87], v[84:85] op_sel_hi:[1,0,1]
	v_cvt_f32_f16_e32 v0, v218
	v_cvt_f32_f16_sdwa v1, v218 dst_sel:DWORD dst_unused:UNUSED_PAD src0_sel:WORD_1
	v_pk_fma_f32 v[86:87], v[134:135], s[86:87], v[86:87] op_sel_hi:[1,0,1]
	v_cvt_f32_f16_e32 v134, v219
	v_cvt_f32_f16_sdwa v135, v219 dst_sel:DWORD dst_unused:UNUSED_PAD src0_sel:WORD_1
	v_pk_fma_f32 v[76:77], v[0:1], s[86:87], v[76:77] op_sel_hi:[1,0,1]
	v_cvt_f32_f16_e32 v0, v216
	v_cvt_f32_f16_sdwa v1, v216 dst_sel:DWORD dst_unused:UNUSED_PAD src0_sel:WORD_1
	v_cvt_f32_f16_e32 v216, v217
	v_cvt_f32_f16_sdwa v217, v217 dst_sel:DWORD dst_unused:UNUSED_PAD src0_sel:WORD_1
	v_pk_fma_f32 v[78:79], v[134:135], s[86:87], v[78:79] op_sel_hi:[1,0,1]
	v_pk_fma_f32 v[68:69], v[0:1], s[86:87], v[68:69] op_sel_hi:[1,0,1]
	v_cvt_f32_f16_e32 v0, v224
	v_pk_fma_f32 v[70:71], v[216:217], s[86:87], v[70:71] op_sel_hi:[1,0,1]
	v_cvt_f32_f16_sdwa v1, v224 dst_sel:DWORD dst_unused:UNUSED_PAD src0_sel:WORD_1
	v_cvt_f32_f16_e32 v216, v225
	v_cvt_f32_f16_sdwa v217, v225 dst_sel:DWORD dst_unused:UNUSED_PAD src0_sel:WORD_1
	v_pk_fma_f32 v[96:97], v[0:1], s[86:87], v[96:97] op_sel_hi:[1,0,1]
	v_cvt_f32_f16_e32 v0, v226
	v_pk_fma_f32 v[98:99], v[216:217], s[86:87], v[98:99] op_sel_hi:[1,0,1]
	v_cvt_f32_f16_sdwa v1, v226 dst_sel:DWORD dst_unused:UNUSED_PAD src0_sel:WORD_1
	v_cvt_f32_f16_e32 v216, v227
	v_cvt_f32_f16_sdwa v217, v227 dst_sel:DWORD dst_unused:UNUSED_PAD src0_sel:WORD_1
	v_mov_b32_e32 v143, v3
	v_pk_fma_f32 v[88:89], v[0:1], s[86:87], v[88:89] op_sel_hi:[1,0,1]
	v_cvt_f32_f16_e32 v0, v228
	v_pk_fma_f32 v[90:91], v[216:217], s[86:87], v[90:91] op_sel_hi:[1,0,1]
	v_cvt_f32_f16_sdwa v1, v228 dst_sel:DWORD dst_unused:UNUSED_PAD src0_sel:WORD_1
	v_cvt_f32_f16_e32 v216, v229
	v_cvt_f32_f16_sdwa v217, v229 dst_sel:DWORD dst_unused:UNUSED_PAD src0_sel:WORD_1
	v_mov_b32_e32 v138, v3
	v_pk_fma_f32 v[80:81], v[0:1], s[86:87], v[80:81] op_sel_hi:[1,0,1]
	v_cvt_f32_f16_e32 v0, v230
	v_pk_fma_f32 v[82:83], v[216:217], s[86:87], v[82:83] op_sel_hi:[1,0,1]
	v_cvt_f32_f16_sdwa v1, v230 dst_sel:DWORD dst_unused:UNUSED_PAD src0_sel:WORD_1
	v_cvt_f32_f16_e32 v216, v231
	v_cvt_f32_f16_sdwa v217, v231 dst_sel:DWORD dst_unused:UNUSED_PAD src0_sel:WORD_1
	v_mov_b32_e32 v139, v3
	v_pk_fma_f32 v[72:73], v[0:1], s[86:87], v[72:73] op_sel_hi:[1,0,1]
	v_add_u32_e32 v0, 0x28000, v2
	v_pk_fma_f32 v[74:75], v[216:217], s[86:87], v[74:75] op_sel_hi:[1,0,1]
	v_mov_b32_e32 v1, v3
	v_add_u32_e32 v2, 0x2c000, v2
	v_lshl_add_u64 v[132:133], v[0:1], 1, s[2:3]
	v_lshl_add_u64 v[134:135], v[2:3], 1, s[2:3]
	global_load_dwordx2 v[0:1], v[132:133], off
	global_load_dwordx2 v[140:141], v[132:133], off offset:32
	global_load_dwordx2 v[136:137], v[132:133], off offset:256
	s_nop 0
	global_load_dwordx2 v[132:133], v[132:133], off offset:288
	s_nop 0
	global_load_dwordx2 v[144:145], v[134:135], off
	global_load_dwordx2 v[150:151], v[134:135], off offset:32
	global_load_dwordx2 v[178:179], v[134:135], off offset:256
	global_load_dwordx2 v[182:183], v[134:135], off offset:288
	v_mov_b32_e32 v2, v3
	v_mov_b32_e32 v134, v3
	v_mov_b32_e32 v135, v3
	v_mov_b32_e32 v146, v3
	v_mov_b32_e32 v147, v3
	v_mov_b32_e32 v152, v3
	v_mov_b32_e32 v153, v3
	v_mov_b32_e32 v180, v3
	v_mov_b32_e32 v181, v3
	v_mov_b32_e32 v184, v3
	v_mov_b32_e32 v185, v3
	s_lshl_b32 s2, s14, 3
	s_add_i32 s7, s2, 0
	s_waitcnt vmcnt(7)
	v_mov_b64_e32 v[188:189], v[2:3]
	v_mov_b64_e32 v[186:187], v[0:1]
	s_waitcnt vmcnt(0)
	s_nop 0
	v_cvt_f32_f16_e32 v0, v186
	v_cvt_f32_f16_sdwa v1, v186 dst_sel:DWORD dst_unused:UNUSED_PAD src0_sel:WORD_1
	v_cvt_f32_f16_e32 v134, v187
	v_cvt_f32_f16_sdwa v135, v187 dst_sel:DWORD dst_unused:UNUSED_PAD src0_sel:WORD_1
	v_xor_b32_e32 v2, 32, v171
	v_pk_fma_f32 v[124:125], v[0:1], s[86:87], v[124:125] op_sel_hi:[1,0,1]
	v_cvt_f32_f16_e32 v0, v140
	v_cvt_f32_f16_sdwa v1, v140 dst_sel:DWORD dst_unused:UNUSED_PAD src0_sel:WORD_1
	v_pk_fma_f32 v[126:127], v[134:135], s[86:87], v[126:127] op_sel_hi:[1,0,1]
	v_cvt_f32_f16_e32 v134, v141
	v_cvt_f32_f16_sdwa v135, v141 dst_sel:DWORD dst_unused:UNUSED_PAD src0_sel:WORD_1
	v_pk_fma_f32 v[116:117], v[0:1], s[86:87], v[116:117] op_sel_hi:[1,0,1]
	v_cvt_f32_f16_e32 v0, v136
	v_cvt_f32_f16_sdwa v1, v136 dst_sel:DWORD dst_unused:UNUSED_PAD src0_sel:WORD_1
	v_pk_fma_f32 v[118:119], v[134:135], s[86:87], v[118:119] op_sel_hi:[1,0,1]
	v_cvt_f32_f16_e32 v134, v137
	v_cvt_f32_f16_sdwa v135, v137 dst_sel:DWORD dst_unused:UNUSED_PAD src0_sel:WORD_1
	v_pk_fma_f32 v[108:109], v[0:1], s[86:87], v[108:109] op_sel_hi:[1,0,1]
	v_cvt_f32_f16_e32 v0, v132
	v_cvt_f32_f16_sdwa v1, v132 dst_sel:DWORD dst_unused:UNUSED_PAD src0_sel:WORD_1
	v_cvt_f32_f16_e32 v132, v133
	v_cvt_f32_f16_sdwa v133, v133 dst_sel:DWORD dst_unused:UNUSED_PAD src0_sel:WORD_1
	v_pk_fma_f32 v[110:111], v[134:135], s[86:87], v[110:111] op_sel_hi:[1,0,1]
	v_pk_fma_f32 v[100:101], v[0:1], s[86:87], v[100:101] op_sel_hi:[1,0,1]
	v_cvt_f32_f16_e32 v0, v144
	v_cvt_f32_f16_sdwa v1, v144 dst_sel:DWORD dst_unused:UNUSED_PAD src0_sel:WORD_1
	v_pk_fma_f32 v[102:103], v[132:133], s[86:87], v[102:103] op_sel_hi:[1,0,1]
	v_cvt_f32_f16_e32 v132, v145
	v_cvt_f32_f16_sdwa v133, v145 dst_sel:DWORD dst_unused:UNUSED_PAD src0_sel:WORD_1
	v_pk_fma_f32 v[128:129], v[0:1], s[86:87], v[128:129] op_sel_hi:[1,0,1]
	v_cvt_f32_f16_e32 v0, v150
	v_cvt_f32_f16_sdwa v1, v150 dst_sel:DWORD dst_unused:UNUSED_PAD src0_sel:WORD_1
	v_pk_fma_f32 v[130:131], v[132:133], s[86:87], v[130:131] op_sel_hi:[1,0,1]
	v_cvt_f32_f16_e32 v132, v151
	v_cvt_f32_f16_sdwa v133, v151 dst_sel:DWORD dst_unused:UNUSED_PAD src0_sel:WORD_1
	v_pk_fma_f32 v[120:121], v[0:1], s[86:87], v[120:121] op_sel_hi:[1,0,1]
	v_cvt_f32_f16_e32 v0, v178
	v_cvt_f32_f16_sdwa v1, v178 dst_sel:DWORD dst_unused:UNUSED_PAD src0_sel:WORD_1
	v_pk_fma_f32 v[122:123], v[132:133], s[86:87], v[122:123] op_sel_hi:[1,0,1]
	v_cvt_f32_f16_e32 v132, v179
	v_cvt_f32_f16_sdwa v133, v179 dst_sel:DWORD dst_unused:UNUSED_PAD src0_sel:WORD_1
	v_pk_fma_f32 v[112:113], v[0:1], s[86:87], v[112:113] op_sel_hi:[1,0,1]
	v_cvt_f32_f16_e32 v0, v182
	v_cvt_f32_f16_sdwa v1, v182 dst_sel:DWORD dst_unused:UNUSED_PAD src0_sel:WORD_1
	v_pk_fma_f32 v[114:115], v[132:133], s[86:87], v[114:115] op_sel_hi:[1,0,1]
	v_cvt_f32_f16_e32 v132, v183
	v_cvt_f32_f16_sdwa v133, v183 dst_sel:DWORD dst_unused:UNUSED_PAD src0_sel:WORD_1
	v_pk_fma_f32 v[104:105], v[0:1], s[86:87], v[104:105] op_sel_hi:[1,0,1]
	v_and_b32_e32 v1, 64, v171
	v_xor_b32_e32 v0, 16, v171
	v_pk_fma_f32 v[106:107], v[132:133], s[86:87], v[106:107] op_sel_hi:[1,0,1]
	v_add_u32_e32 v1, 64, v1
	v_mov_b32_e32 v132, v29
	v_mov_b32_e32 v133, v30
	v_mov_b32_e32 v134, v28
	v_mov_b32_e32 v135, v31
	v_cmp_lt_i32_e32 vcc, v0, v1
	v_pk_add_f32 v[132:133], v[132:133], v[134:135]
	v_mov_b32_e32 v134, v21
	v_mov_b32_e32 v135, v22
	v_mov_b32_e32 v136, v20
	v_mov_b32_e32 v137, v23
	v_cndmask_b32_e32 v0, v171, v0, vcc
	v_cmp_lt_i32_e32 vcc, v2, v1
	v_pk_add_f32 v[134:135], v[134:135], v[136:137]
	v_add_f32_e32 v137, v12, v13
	v_cndmask_b32_e32 v1, v171, v2, vcc
	v_add_f32_e32 v2, v132, v133
	v_pk_add_f32 v[134:135], v[134:135], v[134:135] op_sel_hi:[0,1]
	v_add_f32_e32 v133, 0, v2
	v_add_f32_e32 v139, v14, v15
	v_mov_b32_e32 v136, v4
	v_mov_b32_e32 v138, v5
	v_mov_b32_e32 v134, v6
	v_mov_b32_e32 v132, v7
	v_pk_add_f32 v[136:137], v[136:137], v[138:139]
	v_pk_add_f32 v[132:133], v[134:135], v[132:133]
	v_lshlrev_b32_e32 v0, 2, v0
	v_pk_add_f32 v[132:133], v[136:137], v[132:133]
	v_lshlrev_b32_e32 v1, 2, v1
	v_add_f32_e32 v2, v132, v133
	ds_bpermute_b32 v132, v0, v2
	v_cmp_gt_u32_e32 vcc, 16, v149
	s_waitcnt lgkmcnt(0)
	v_add_f32_e32 v2, v2, v132
	ds_bpermute_b32 v132, v1, v2
	s_waitcnt lgkmcnt(0)
	v_add_f32_e32 v2, v2, v132
	v_fmamk_f32 v133, v2, 0xbc800000, v31
	v_fmamk_f32 v135, v2, 0xbc800000, v29
	v_fmamk_f32 v132, v2, 0xbc800000, v30
	v_fmamk_f32 v134, v2, 0xbc800000, v28
	v_mul_f32_e32 v135, v135, v135
	v_mul_f32_e32 v133, v133, v133
	v_fmac_f32_e32 v135, v134, v134
	v_fmac_f32_e32 v133, v132, v132
	v_fmamk_f32 v134, v2, 0xbc800000, v23
	v_fmamk_f32 v136, v2, 0xbc800000, v21
	v_add_f32_e32 v132, v135, v133
	v_fmamk_f32 v133, v2, 0xbc800000, v22
	v_fmamk_f32 v135, v2, 0xbc800000, v20
	v_mul_f32_e32 v136, v136, v136
	v_mul_f32_e32 v134, v134, v134
	v_fmac_f32_e32 v136, v135, v135
	v_fmac_f32_e32 v134, v133, v133
	v_add_f32_e32 v133, v136, v134
	v_fmamk_f32 v134, v2, 0xbc800000, v15
	v_fmamk_f32 v136, v2, 0xbc800000, v13
	v_add_f32_e32 v132, v132, v133
	v_fmamk_f32 v133, v2, 0xbc800000, v14
	v_fmamk_f32 v135, v2, 0xbc800000, v12
	v_mul_f32_e32 v136, v136, v136
	v_mul_f32_e32 v134, v134, v134
	v_fmac_f32_e32 v136, v135, v135
	v_fmac_f32_e32 v134, v133, v133
	v_add_f32_e32 v133, v136, v134
	v_fmamk_f32 v134, v2, 0xbc800000, v7
	v_fmamk_f32 v136, v2, 0xbc800000, v5
	v_add_f32_e32 v132, v133, v132
	v_fmamk_f32 v133, v2, 0xbc800000, v6
	v_fmamk_f32 v135, v2, 0xbc800000, v4
	v_mul_f32_e32 v136, v136, v136
	v_mul_f32_e32 v134, v134, v134
	v_fmac_f32_e32 v136, v135, v135
	v_fmac_f32_e32 v134, v133, v133
	v_add_f32_e32 v133, v136, v134
	v_add_f32_e32 v132, v133, v132
	ds_bpermute_b32 v133, v0, v132
	s_waitcnt lgkmcnt(0)
	v_add_f32_e32 v132, v132, v133
	ds_bpermute_b32 v133, v1, v132
	s_and_saveexec_b64 s[4:5], vcc
	s_cbranch_execz .LBB0_440
	s_lshl_b32 s2, s80, 11
	s_add_i32 s2, s7, s2
	v_mul_f32_e32 v134, 0x3c800000, v2
	s_waitcnt lgkmcnt(0)
	v_add_f32_e32 v135, v132, v133
	v_lshl_add_u32 v2, v176, 5, s2
	ds_write_b64 v2, v[134:135]

.LBB0_506:
	s_lshl_b32 s2, s14, 5
	s_lshl_b32 s3, s0, 8
	s_or_b32 s2, s3, s2
	v_lshrrev_b32_e32 v0, 2, v148
	s_lshl_b32 s6, s87, 8
	v_and_or_b32 v164, v0, 12, s2
	s_add_i32 s2, s6, s94
	v_or_b32_e32 v0, s2, v176
	v_readlane_b32 s2, v253, 15
	v_lshl_add_u32 v2, v0, 10, v164
	v_readlane_b32 s3, v253, 16
	s_waitcnt vmcnt(0)
	s_barrier
	v_mov_b32_e32 v134, v3
	v_lshl_add_u64 v[0:1], v[2:3], 1, s[2:3]
	global_load_dwordx2 v[132:133], v[0:1], off
	global_load_dwordx2 v[136:137], v[0:1], off offset:32
	global_load_dwordx2 v[140:141], v[0:1], off offset:256
	global_load_dwordx2 v[144:145], v[0:1], off offset:288
	v_add_u32_e32 v0, 0x4000, v2
	v_mov_b32_e32 v1, v3
	v_lshl_add_u64 v[0:1], v[0:1], 1, s[2:3]
	global_load_dwordx2 v[150:151], v[0:1], off
	global_load_dwordx2 v[178:179], v[0:1], off offset:32
	global_load_dwordx2 v[182:183], v[0:1], off offset:256
	global_load_dwordx2 v[186:187], v[0:1], off offset:288
	v_mov_b32_e32 v135, v3
	v_mov_b32_e32 v138, v3
	v_mov_b32_e32 v139, v3
	v_mov_b32_e32 v142, v3
	v_mov_b32_e32 v143, v3
	v_mov_b32_e32 v146, v3
	v_mov_b32_e32 v147, v3
	v_mov_b32_e32 v152, v3
	v_mov_b32_e32 v153, v3
	v_mov_b32_e32 v180, v3
	v_mov_b32_e32 v181, v3
	v_mov_b32_e32 v184, v3
	v_mov_b32_e32 v185, v3
	v_mov_b32_e32 v188, v3
	v_mov_b32_e32 v189, v3
	v_and_b32_e32 v149, 63, v148
	v_add_u32_e32 v0, 0x8000, v2
	v_mov_b32_e32 v1, v3
	v_lshl_add_u64 v[0:1], v[0:1], 1, s[2:3]
	global_load_dwordx2 v[200:201], v[0:1], off
	global_load_dwordx2 v[202:203], v[0:1], off offset:32
	global_load_dwordx2 v[204:205], v[0:1], off offset:256
	global_load_dwordx2 v[206:207], v[0:1], off offset:288
	v_add_u32_e32 v0, 0xc000, v2
	v_mov_b32_e32 v1, v3
	v_lshl_add_u64 v[0:1], v[0:1], 1, s[2:3]
	global_load_dwordx2 v[208:209], v[0:1], off
	global_load_dwordx2 v[210:211], v[0:1], off offset:32
	global_load_dwordx2 v[212:213], v[0:1], off offset:256
	global_load_dwordx2 v[214:215], v[0:1], off offset:288
	v_add_u32_e32 v0, 0x20000, v2
	v_mov_b32_e32 v1, v3
	v_lshl_add_u64 v[0:1], v[0:1], 1, s[2:3]
	global_load_dwordx2 v[222:223], v[0:1], off
	global_load_dwordx2 v[220:221], v[0:1], off offset:32
	global_load_dwordx2 v[218:219], v[0:1], off offset:256
	global_load_dwordx2 v[216:217], v[0:1], off offset:288
	v_add_u32_e32 v0, 0x24000, v2
	v_mov_b32_e32 v1, v3
	v_lshl_add_u64 v[0:1], v[0:1], 1, s[2:3]
	global_load_dwordx2 v[224:225], v[0:1], off
	global_load_dwordx2 v[226:227], v[0:1], off offset:32
	global_load_dwordx2 v[228:229], v[0:1], off offset:256
	global_load_dwordx2 v[230:231], v[0:1], off offset:288
	s_waitcnt vmcnt(16)
	s_nop 0
	v_cvt_f32_f16_e32 v0, v132
	v_cvt_f32_f16_sdwa v1, v132 dst_sel:DWORD dst_unused:UNUSED_PAD src0_sel:WORD_1
	v_cvt_f32_f16_e32 v132, v133
	v_cvt_f32_f16_sdwa v133, v133 dst_sel:DWORD dst_unused:UNUSED_PAD src0_sel:WORD_1
	v_mov_b32_e32 v134, v3
	v_pk_fma_f32 v[28:29], v[0:1], s[86:87], v[28:29] op_sel_hi:[1,0,1]
	v_cvt_f32_f16_e32 v0, v136
	v_pk_fma_f32 v[30:31], v[132:133], s[86:87], v[30:31] op_sel_hi:[1,0,1]
	v_cvt_f32_f16_sdwa v1, v136 dst_sel:DWORD dst_unused:UNUSED_PAD src0_sel:WORD_1
	v_cvt_f32_f16_e32 v132, v137
	v_cvt_f32_f16_sdwa v133, v137 dst_sel:DWORD dst_unused:UNUSED_PAD src0_sel:WORD_1
	v_mov_b32_e32 v135, v3
	v_pk_fma_f32 v[20:21], v[0:1], s[86:87], v[20:21] op_sel_hi:[1,0,1]
	v_cvt_f32_f16_e32 v0, v140
	v_pk_fma_f32 v[22:23], v[132:133], s[86:87], v[22:23] op_sel_hi:[1,0,1]
	v_cvt_f32_f16_sdwa v1, v140 dst_sel:DWORD dst_unused:UNUSED_PAD src0_sel:WORD_1
	v_cvt_f32_f16_e32 v132, v141
	v_cvt_f32_f16_sdwa v133, v141 dst_sel:DWORD dst_unused:UNUSED_PAD src0_sel:WORD_1
	v_mov_b32_e32 v138, v3
	v_pk_fma_f32 v[12:13], v[0:1], s[86:87], v[12:13] op_sel_hi:[1,0,1]
	v_cvt_f32_f16_e32 v0, v144
	v_pk_fma_f32 v[14:15], v[132:133], s[86:87], v[14:15] op_sel_hi:[1,0,1]
	v_cvt_f32_f16_sdwa v1, v144 dst_sel:DWORD dst_unused:UNUSED_PAD src0_sel:WORD_1
	v_cvt_f32_f16_e32 v132, v145
	v_cvt_f32_f16_sdwa v133, v145 dst_sel:DWORD dst_unused:UNUSED_PAD src0_sel:WORD_1
	v_mov_b32_e32 v139, v3
	v_pk_fma_f32 v[4:5], v[0:1], s[86:87], v[4:5] op_sel_hi:[1,0,1]
	v_cvt_f32_f16_e32 v0, v150
	v_pk_fma_f32 v[6:7], v[132:133], s[86:87], v[6:7] op_sel_hi:[1,0,1]
	v_cvt_f32_f16_sdwa v1, v150 dst_sel:DWORD dst_unused:UNUSED_PAD src0_sel:WORD_1
	v_cvt_f32_f16_e32 v132, v151
	v_cvt_f32_f16_sdwa v133, v151 dst_sel:DWORD dst_unused:UNUSED_PAD src0_sel:WORD_1
	v_pk_fma_f32 v[32:33], v[0:1], s[86:87], v[32:33] op_sel_hi:[1,0,1]
	v_cvt_f32_f16_e32 v0, v178
	v_pk_fma_f32 v[34:35], v[132:133], s[86:87], v[34:35] op_sel_hi:[1,0,1]
	v_cvt_f32_f16_sdwa v1, v178 dst_sel:DWORD dst_unused:UNUSED_PAD src0_sel:WORD_1
	v_cvt_f32_f16_e32 v132, v179
	v_cvt_f32_f16_sdwa v133, v179 dst_sel:DWORD dst_unused:UNUSED_PAD src0_sel:WORD_1
	v_mov_b32_e32 v142, v3
	v_pk_fma_f32 v[24:25], v[0:1], s[86:87], v[24:25] op_sel_hi:[1,0,1]
	v_cvt_f32_f16_e32 v0, v182
	v_pk_fma_f32 v[26:27], v[132:133], s[86:87], v[26:27] op_sel_hi:[1,0,1]
	v_cvt_f32_f16_sdwa v1, v182 dst_sel:DWORD dst_unused:UNUSED_PAD src0_sel:WORD_1
	v_cvt_f32_f16_e32 v132, v183
	v_cvt_f32_f16_sdwa v133, v183 dst_sel:DWORD dst_unused:UNUSED_PAD src0_sel:WORD_1
	v_mov_b32_e32 v143, v3
	v_pk_fma_f32 v[16:17], v[0:1], s[86:87], v[16:17] op_sel_hi:[1,0,1]
	v_cvt_f32_f16_e32 v0, v186
	v_pk_fma_f32 v[18:19], v[132:133], s[86:87], v[18:19] op_sel_hi:[1,0,1]
	v_cvt_f32_f16_sdwa v1, v186 dst_sel:DWORD dst_unused:UNUSED_PAD src0_sel:WORD_1
	v_cvt_f32_f16_e32 v132, v187
	v_cvt_f32_f16_sdwa v133, v187 dst_sel:DWORD dst_unused:UNUSED_PAD src0_sel:WORD_1
	v_mov_b32_e32 v146, v3
	v_pk_fma_f32 v[8:9], v[0:1], s[86:87], v[8:9] op_sel_hi:[1,0,1]
	v_pk_fma_f32 v[10:11], v[132:133], s[86:87], v[10:11] op_sel_hi:[1,0,1]
	v_mov_b32_e32 v147, v3
	v_mov_b32_e32 v152, v3
	v_mov_b32_e32 v153, v3
	v_mov_b32_e32 v180, v3
	v_mov_b32_e32 v181, v3
	v_mov_b32_e32 v184, v3
	v_mov_b32_e32 v185, v3
	v_mov_b32_e32 v188, v3
	v_mov_b32_e32 v189, v3
	s_waitcnt vmcnt(8)
	s_nop 0
	v_cvt_f32_f16_e32 v0, v200
	v_cvt_f32_f16_sdwa v1, v200 dst_sel:DWORD dst_unused:UNUSED_PAD src0_sel:WORD_1
	v_cvt_f32_f16_e32 v200, v201
	v_cvt_f32_f16_sdwa v201, v201 dst_sel:DWORD dst_unused:UNUSED_PAD src0_sel:WORD_1
	v_mov_b32_e32 v146, v3
	v_pk_fma_f32 v[60:61], v[0:1], s[86:87], v[60:61] op_sel_hi:[1,0,1]
	v_cvt_f32_f16_e32 v0, v202
	v_pk_fma_f32 v[62:63], v[200:201], s[86:87], v[62:63] op_sel_hi:[1,0,1]
	v_cvt_f32_f16_sdwa v1, v202 dst_sel:DWORD dst_unused:UNUSED_PAD src0_sel:WORD_1
	v_cvt_f32_f16_e32 v200, v203
	v_cvt_f32_f16_sdwa v201, v203 dst_sel:DWORD dst_unused:UNUSED_PAD src0_sel:WORD_1
	v_mov_b32_e32 v147, v3
	v_pk_fma_f32 v[52:53], v[0:1], s[86:87], v[52:53] op_sel_hi:[1,0,1]
	v_cvt_f32_f16_e32 v0, v204
	v_pk_fma_f32 v[54:55], v[200:201], s[86:87], v[54:55] op_sel_hi:[1,0,1]
	v_cvt_f32_f16_sdwa v1, v204 dst_sel:DWORD dst_unused:UNUSED_PAD src0_sel:WORD_1
	v_cvt_f32_f16_e32 v200, v205
	v_cvt_f32_f16_sdwa v201, v205 dst_sel:DWORD dst_unused:UNUSED_PAD src0_sel:WORD_1
	v_mov_b32_e32 v142, v3
	v_pk_fma_f32 v[44:45], v[0:1], s[86:87], v[44:45] op_sel_hi:[1,0,1]
	v_cvt_f32_f16_e32 v0, v206
	v_pk_fma_f32 v[46:47], v[200:201], s[86:87], v[46:47] op_sel_hi:[1,0,1]
	v_cvt_f32_f16_sdwa v1, v206 dst_sel:DWORD dst_unused:UNUSED_PAD src0_sel:WORD_1
	v_cvt_f32_f16_e32 v200, v207
	v_cvt_f32_f16_sdwa v201, v207 dst_sel:DWORD dst_unused:UNUSED_PAD src0_sel:WORD_1
	v_mov_b32_e32 v143, v3
	v_pk_fma_f32 v[36:37], v[0:1], s[86:87], v[36:37] op_sel_hi:[1,0,1]
	v_cvt_f32_f16_e32 v0, v208
	v_pk_fma_f32 v[38:39], v[200:201], s[86:87], v[38:39] op_sel_hi:[1,0,1]
	v_cvt_f32_f16_sdwa v1, v208 dst_sel:DWORD dst_unused:UNUSED_PAD src0_sel:WORD_1
	v_cvt_f32_f16_e32 v200, v209
	v_cvt_f32_f16_sdwa v201, v209 dst_sel:DWORD dst_unused:UNUSED_PAD src0_sel:WORD_1
	v_pk_fma_f32 v[64:65], v[0:1], s[86:87], v[64:65] op_sel_hi:[1,0,1]
	v_cvt_f32_f16_e32 v0, v210
	v_pk_fma_f32 v[66:67], v[200:201], s[86:87], v[66:67] op_sel_hi:[1,0,1]
	v_cvt_f32_f16_sdwa v1, v210 dst_sel:DWORD dst_unused:UNUSED_PAD src0_sel:WORD_1
	v_cvt_f32_f16_e32 v200, v211
	v_cvt_f32_f16_sdwa v201, v211 dst_sel:DWORD dst_unused:UNUSED_PAD src0_sel:WORD_1
	v_mov_b32_e32 v138, v3
	v_pk_fma_f32 v[56:57], v[0:1], s[86:87], v[56:57] op_sel_hi:[1,0,1]
	v_cvt_f32_f16_e32 v0, v212
	v_pk_fma_f32 v[58:59], v[200:201], s[86:87], v[58:59] op_sel_hi:[1,0,1]
	v_cvt_f32_f16_sdwa v1, v212 dst_sel:DWORD dst_unused:UNUSED_PAD src0_sel:WORD_1
	v_cvt_f32_f16_e32 v200, v213
	v_cvt_f32_f16_sdwa v201, v213 dst_sel:DWORD dst_unused:UNUSED_PAD src0_sel:WORD_1
	v_mov_b32_e32 v139, v3
	v_pk_fma_f32 v[48:49], v[0:1], s[86:87], v[48:49] op_sel_hi:[1,0,1]
	v_cvt_f32_f16_e32 v0, v214
	v_pk_fma_f32 v[50:51], v[200:201], s[86:87], v[50:51] op_sel_hi:[1,0,1]
	v_cvt_f32_f16_sdwa v1, v214 dst_sel:DWORD dst_unused:UNUSED_PAD src0_sel:WORD_1
	v_cvt_f32_f16_e32 v200, v215
	v_cvt_f32_f16_sdwa v201, v215 dst_sel:DWORD dst_unused:UNUSED_PAD src0_sel:WORD_1
	v_mov_b32_e32 v134, v3
	v_pk_fma_f32 v[40:41], v[0:1], s[86:87], v[40:41] op_sel_hi:[1,0,1]
	v_pk_fma_f32 v[42:43], v[200:201], s[86:87], v[42:43] op_sel_hi:[1,0,1]
	v_mov_b32_e32 v135, v3
	v_mov_b32_e32 v152, v3
	v_mov_b32_e32 v153, v3
	v_mov_b32_e32 v180, v3
	v_mov_b32_e32 v181, v3
	v_mov_b32_e32 v184, v3
	v_mov_b32_e32 v185, v3
	v_mov_b32_e32 v188, v3
	v_mov_b32_e32 v189, v3
	s_waitcnt vmcnt(0)
	s_nop 0
	v_cvt_f32_f16_e32 v0, v222
	v_cvt_f32_f16_sdwa v1, v222 dst_sel:DWORD dst_unused:UNUSED_PAD src0_sel:WORD_1
	v_cvt_f32_f16_e32 v134, v223
	v_cvt_f32_f16_sdwa v135, v223 dst_sel:DWORD dst_unused:UNUSED_PAD src0_sel:WORD_1
	v_mov_b32_e32 v142, v3
	v_pk_fma_f32 v[92:93], v[0:1], s[86:87], v[92:93] op_sel_hi:[1,0,1]
	v_cvt_f32_f16_e32 v0, v220
	v_cvt_f32_f16_sdwa v1, v220 dst_sel:DWORD dst_unused:UNUSED_PAD src0_sel:WORD_1
	v_pk_fma_f32 v[94:95], v[134:135], s[86:87], v[94:95] op_sel_hi:[1,0,1]
	v_cvt_f32_f16_e32 v134, v221
	v_cvt_f32_f16_sdwa v135, v221 dst_sel:DWORD dst_unused:UNUSED_PAD src0_sel:WORD_1
	v_pk_fma_f32 v[84:85], v[0:1], s[86:87], v[84:85] op_sel_hi:[1,0,1]
	v_cvt_f32_f16_e32 v0, v218
	v_cvt_f32_f16_sdwa v1, v218 dst_sel:DWORD dst_unused:UNUSED_PAD src0_sel:WORD_1
	v_pk_fma_f32 v[86:87], v[134:135], s[86:87], v[86:87] op_sel_hi:[1,0,1]
	v_cvt_f32_f16_e32 v134, v219
	v_cvt_f32_f16_sdwa v135, v219 dst_sel:DWORD dst_unused:UNUSED_PAD src0_sel:WORD_1
	v_pk_fma_f32 v[76:77], v[0:1], s[86:87], v[76:77] op_sel_hi:[1,0,1]
	v_cvt_f32_f16_e32 v0, v216
	v_cvt_f32_f16_sdwa v1, v216 dst_sel:DWORD dst_unused:UNUSED_PAD src0_sel:WORD_1
	v_cvt_f32_f16_e32 v216, v217
	v_cvt_f32_f16_sdwa v217, v217 dst_sel:DWORD dst_unused:UNUSED_PAD src0_sel:WORD_1
	v_pk_fma_f32 v[78:79], v[134:135], s[86:87], v[78:79] op_sel_hi:[1,0,1]
	v_pk_fma_f32 v[68:69], v[0:1], s[86:87], v[68:69] op_sel_hi:[1,0,1]
	v_cvt_f32_f16_e32 v0, v224
	v_pk_fma_f32 v[70:71], v[216:217], s[86:87], v[70:71] op_sel_hi:[1,0,1]
	v_cvt_f32_f16_sdwa v1, v224 dst_sel:DWORD dst_unused:UNUSED_PAD src0_sel:WORD_1
	v_cvt_f32_f16_e32 v216, v225
	v_cvt_f32_f16_sdwa v217, v225 dst_sel:DWORD dst_unused:UNUSED_PAD src0_sel:WORD_1
	v_pk_fma_f32 v[96:97], v[0:1], s[86:87], v[96:97] op_sel_hi:[1,0,1]
	v_cvt_f32_f16_e32 v0, v226
	v_pk_fma_f32 v[98:99], v[216:217], s[86:87], v[98:99] op_sel_hi:[1,0,1]
	v_cvt_f32_f16_sdwa v1, v226 dst_sel:DWORD dst_unused:UNUSED_PAD src0_sel:WORD_1
	v_cvt_f32_f16_e32 v216, v227
	v_cvt_f32_f16_sdwa v217, v227 dst_sel:DWORD dst_unused:UNUSED_PAD src0_sel:WORD_1
	v_mov_b32_e32 v143, v3
	v_pk_fma_f32 v[88:89], v[0:1], s[86:87], v[88:89] op_sel_hi:[1,0,1]
	v_cvt_f32_f16_e32 v0, v228
	v_pk_fma_f32 v[90:91], v[216:217], s[86:87], v[90:91] op_sel_hi:[1,0,1]
	v_cvt_f32_f16_sdwa v1, v228 dst_sel:DWORD dst_unused:UNUSED_PAD src0_sel:WORD_1
	v_cvt_f32_f16_e32 v216, v229
	v_cvt_f32_f16_sdwa v217, v229 dst_sel:DWORD dst_unused:UNUSED_PAD src0_sel:WORD_1
	v_mov_b32_e32 v138, v3
	v_pk_fma_f32 v[80:81], v[0:1], s[86:87], v[80:81] op_sel_hi:[1,0,1]
	v_cvt_f32_f16_e32 v0, v230
	v_pk_fma_f32 v[82:83], v[216:217], s[86:87], v[82:83] op_sel_hi:[1,0,1]
	v_cvt_f32_f16_sdwa v1, v230 dst_sel:DWORD dst_unused:UNUSED_PAD src0_sel:WORD_1
	v_cvt_f32_f16_e32 v216, v231
	v_cvt_f32_f16_sdwa v217, v231 dst_sel:DWORD dst_unused:UNUSED_PAD src0_sel:WORD_1
	v_mov_b32_e32 v139, v3
	v_pk_fma_f32 v[72:73], v[0:1], s[86:87], v[72:73] op_sel_hi:[1,0,1]
	v_add_u32_e32 v0, 0x28000, v2
	v_pk_fma_f32 v[74:75], v[216:217], s[86:87], v[74:75] op_sel_hi:[1,0,1]
	v_mov_b32_e32 v1, v3
	v_add_u32_e32 v2, 0x2c000, v2
	v_lshl_add_u64 v[132:133], v[0:1], 1, s[2:3]
	v_lshl_add_u64 v[134:135], v[2:3], 1, s[2:3]
	global_load_dwordx2 v[0:1], v[132:133], off
	global_load_dwordx2 v[140:141], v[132:133], off offset:32
	global_load_dwordx2 v[136:137], v[132:133], off offset:256
	s_nop 0
	global_load_dwordx2 v[132:133], v[132:133], off offset:288
	s_nop 0
	global_load_dwordx2 v[144:145], v[134:135], off
	global_load_dwordx2 v[150:151], v[134:135], off offset:32
	global_load_dwordx2 v[178:179], v[134:135], off offset:256
	global_load_dwordx2 v[182:183], v[134:135], off offset:288
	v_mov_b32_e32 v2, v3
	v_mov_b32_e32 v134, v3
	v_mov_b32_e32 v135, v3
	v_mov_b32_e32 v146, v3
	v_mov_b32_e32 v147, v3
	v_mov_b32_e32 v152, v3
	v_mov_b32_e32 v153, v3
	v_mov_b32_e32 v180, v3
	v_mov_b32_e32 v181, v3
	v_mov_b32_e32 v184, v3
	v_mov_b32_e32 v185, v3
	s_lshl_b32 s2, s14, 3
	s_add_i32 s7, s2, 0
	s_waitcnt vmcnt(7)
	v_mov_b64_e32 v[188:189], v[2:3]
	v_mov_b64_e32 v[186:187], v[0:1]
	s_waitcnt vmcnt(0)
	s_nop 0
	v_cvt_f32_f16_e32 v0, v186
	v_cvt_f32_f16_sdwa v1, v186 dst_sel:DWORD dst_unused:UNUSED_PAD src0_sel:WORD_1
	v_cvt_f32_f16_e32 v134, v187
	v_cvt_f32_f16_sdwa v135, v187 dst_sel:DWORD dst_unused:UNUSED_PAD src0_sel:WORD_1
	v_xor_b32_e32 v2, 32, v171
	v_pk_fma_f32 v[124:125], v[0:1], s[86:87], v[124:125] op_sel_hi:[1,0,1]
	v_cvt_f32_f16_e32 v0, v140
	v_cvt_f32_f16_sdwa v1, v140 dst_sel:DWORD dst_unused:UNUSED_PAD src0_sel:WORD_1
	v_pk_fma_f32 v[126:127], v[134:135], s[86:87], v[126:127] op_sel_hi:[1,0,1]
	v_cvt_f32_f16_e32 v134, v141
	v_cvt_f32_f16_sdwa v135, v141 dst_sel:DWORD dst_unused:UNUSED_PAD src0_sel:WORD_1
	v_pk_fma_f32 v[116:117], v[0:1], s[86:87], v[116:117] op_sel_hi:[1,0,1]
	v_cvt_f32_f16_e32 v0, v136
	v_cvt_f32_f16_sdwa v1, v136 dst_sel:DWORD dst_unused:UNUSED_PAD src0_sel:WORD_1
	v_pk_fma_f32 v[118:119], v[134:135], s[86:87], v[118:119] op_sel_hi:[1,0,1]
	v_cvt_f32_f16_e32 v134, v137
	v_cvt_f32_f16_sdwa v135, v137 dst_sel:DWORD dst_unused:UNUSED_PAD src0_sel:WORD_1
	v_pk_fma_f32 v[108:109], v[0:1], s[86:87], v[108:109] op_sel_hi:[1,0,1]
	v_cvt_f32_f16_e32 v0, v132
	v_cvt_f32_f16_sdwa v1, v132 dst_sel:DWORD dst_unused:UNUSED_PAD src0_sel:WORD_1
	v_cvt_f32_f16_e32 v132, v133
	v_cvt_f32_f16_sdwa v133, v133 dst_sel:DWORD dst_unused:UNUSED_PAD src0_sel:WORD_1
	v_pk_fma_f32 v[110:111], v[134:135], s[86:87], v[110:111] op_sel_hi:[1,0,1]
	v_pk_fma_f32 v[100:101], v[0:1], s[86:87], v[100:101] op_sel_hi:[1,0,1]
	v_cvt_f32_f16_e32 v0, v144
	v_cvt_f32_f16_sdwa v1, v144 dst_sel:DWORD dst_unused:UNUSED_PAD src0_sel:WORD_1
	v_pk_fma_f32 v[102:103], v[132:133], s[86:87], v[102:103] op_sel_hi:[1,0,1]
	v_cvt_f32_f16_e32 v132, v145
	v_cvt_f32_f16_sdwa v133, v145 dst_sel:DWORD dst_unused:UNUSED_PAD src0_sel:WORD_1
	v_pk_fma_f32 v[128:129], v[0:1], s[86:87], v[128:129] op_sel_hi:[1,0,1]
	v_cvt_f32_f16_e32 v0, v150
	v_cvt_f32_f16_sdwa v1, v150 dst_sel:DWORD dst_unused:UNUSED_PAD src0_sel:WORD_1
	v_pk_fma_f32 v[130:131], v[132:133], s[86:87], v[130:131] op_sel_hi:[1,0,1]
	v_cvt_f32_f16_e32 v132, v151
	v_cvt_f32_f16_sdwa v133, v151 dst_sel:DWORD dst_unused:UNUSED_PAD src0_sel:WORD_1
	v_pk_fma_f32 v[120:121], v[0:1], s[86:87], v[120:121] op_sel_hi:[1,0,1]
	v_cvt_f32_f16_e32 v0, v178
	v_cvt_f32_f16_sdwa v1, v178 dst_sel:DWORD dst_unused:UNUSED_PAD src0_sel:WORD_1
	v_pk_fma_f32 v[122:123], v[132:133], s[86:87], v[122:123] op_sel_hi:[1,0,1]
	v_cvt_f32_f16_e32 v132, v179
	v_cvt_f32_f16_sdwa v133, v179 dst_sel:DWORD dst_unused:UNUSED_PAD src0_sel:WORD_1
	v_pk_fma_f32 v[112:113], v[0:1], s[86:87], v[112:113] op_sel_hi:[1,0,1]
	v_cvt_f32_f16_e32 v0, v182
	v_cvt_f32_f16_sdwa v1, v182 dst_sel:DWORD dst_unused:UNUSED_PAD src0_sel:WORD_1
	v_pk_fma_f32 v[114:115], v[132:133], s[86:87], v[114:115] op_sel_hi:[1,0,1]
	v_cvt_f32_f16_e32 v132, v183
	v_cvt_f32_f16_sdwa v133, v183 dst_sel:DWORD dst_unused:UNUSED_PAD src0_sel:WORD_1
	v_pk_fma_f32 v[104:105], v[0:1], s[86:87], v[104:105] op_sel_hi:[1,0,1]
	v_and_b32_e32 v1, 64, v171
	v_xor_b32_e32 v0, 16, v171
	v_pk_fma_f32 v[106:107], v[132:133], s[86:87], v[106:107] op_sel_hi:[1,0,1]
	v_add_u32_e32 v1, 64, v1
	v_mov_b32_e32 v132, v29
	v_mov_b32_e32 v133, v30
	v_mov_b32_e32 v134, v28
	v_mov_b32_e32 v135, v31
	v_cmp_lt_i32_e32 vcc, v0, v1
	v_pk_add_f32 v[132:133], v[132:133], v[134:135]
	v_mov_b32_e32 v134, v21
	v_mov_b32_e32 v135, v22
	v_mov_b32_e32 v136, v20
	v_mov_b32_e32 v137, v23
	v_cndmask_b32_e32 v0, v171, v0, vcc
	v_cmp_lt_i32_e32 vcc, v2, v1
	v_pk_add_f32 v[134:135], v[134:135], v[136:137]
	v_add_f32_e32 v137, v12, v13
	v_cndmask_b32_e32 v1, v171, v2, vcc
	v_add_f32_e32 v2, v132, v133
	v_pk_add_f32 v[134:135], v[134:135], v[134:135] op_sel_hi:[0,1]
	v_add_f32_e32 v133, 0, v2
	v_add_f32_e32 v139, v14, v15
	v_mov_b32_e32 v136, v4
	v_mov_b32_e32 v138, v5
	v_mov_b32_e32 v134, v6
	v_mov_b32_e32 v132, v7
	v_pk_add_f32 v[136:137], v[136:137], v[138:139]
	v_pk_add_f32 v[132:133], v[134:135], v[132:133]
	v_lshlrev_b32_e32 v0, 2, v0
	v_pk_add_f32 v[132:133], v[136:137], v[132:133]
	v_lshlrev_b32_e32 v1, 2, v1
	v_add_f32_e32 v2, v132, v133
	ds_bpermute_b32 v132, v0, v2
	v_cmp_gt_u32_e32 vcc, 16, v149
	s_waitcnt lgkmcnt(0)
	v_add_f32_e32 v2, v2, v132
	ds_bpermute_b32 v132, v1, v2
	s_waitcnt lgkmcnt(0)
	v_add_f32_e32 v2, v2, v132
	v_fmamk_f32 v133, v2, 0xbc800000, v31
	v_fmamk_f32 v135, v2, 0xbc800000, v29
	v_fmamk_f32 v132, v2, 0xbc800000, v30
	v_fmamk_f32 v134, v2, 0xbc800000, v28
	v_mul_f32_e32 v135, v135, v135
	v_mul_f32_e32 v133, v133, v133
	v_fmac_f32_e32 v135, v134, v134
	v_fmac_f32_e32 v133, v132, v132
	v_fmamk_f32 v134, v2, 0xbc800000, v23
	v_fmamk_f32 v136, v2, 0xbc800000, v21
	v_add_f32_e32 v132, v135, v133
	v_fmamk_f32 v133, v2, 0xbc800000, v22
	v_fmamk_f32 v135, v2, 0xbc800000, v20
	v_mul_f32_e32 v136, v136, v136
	v_mul_f32_e32 v134, v134, v134
	v_fmac_f32_e32 v136, v135, v135
	v_fmac_f32_e32 v134, v133, v133
	v_add_f32_e32 v133, v136, v134
	v_fmamk_f32 v134, v2, 0xbc800000, v15
	v_fmamk_f32 v136, v2, 0xbc800000, v13
	v_add_f32_e32 v132, v132, v133
	v_fmamk_f32 v133, v2, 0xbc800000, v14
	v_fmamk_f32 v135, v2, 0xbc800000, v12
	v_mul_f32_e32 v136, v136, v136
	v_mul_f32_e32 v134, v134, v134
	v_fmac_f32_e32 v136, v135, v135
	v_fmac_f32_e32 v134, v133, v133
	v_add_f32_e32 v133, v136, v134
	v_fmamk_f32 v134, v2, 0xbc800000, v7
	v_fmamk_f32 v136, v2, 0xbc800000, v5
	v_add_f32_e32 v132, v133, v132
	v_fmamk_f32 v133, v2, 0xbc800000, v6
	v_fmamk_f32 v135, v2, 0xbc800000, v4
	v_mul_f32_e32 v136, v136, v136
	v_mul_f32_e32 v134, v134, v134
	v_fmac_f32_e32 v136, v135, v135
	v_fmac_f32_e32 v134, v133, v133
	v_add_f32_e32 v133, v136, v134
	v_add_f32_e32 v132, v133, v132
	ds_bpermute_b32 v133, v0, v132
	s_waitcnt lgkmcnt(0)
	v_add_f32_e32 v132, v132, v133
	ds_bpermute_b32 v133, v1, v132
	s_and_saveexec_b64 s[4:5], vcc
	s_cbranch_execz .LBB0_508
	s_lshl_b32 s2, s80, 11
	s_add_i32 s2, s7, s2
	v_mul_f32_e32 v134, 0x3c800000, v2
	s_waitcnt lgkmcnt(0)
	v_add_f32_e32 v135, v132, v133
	v_lshl_add_u32 v2, v176, 5, s2
	ds_write_b64 v2, v[134:135]

.LBB0_1154:
	s_lshl_b32 s4, s8, 5
	s_lshl_b32 s5, s44, 8
	s_or_b32 s4, s5, s4
	v_lshrrev_b32_e32 v0, 2, v145
	s_lshl_b32 s6, s1, 8
	v_and_or_b32 v140, v0, 12, s4
	s_add_i32 s4, s6, s14
	v_or_b32_e32 v0, s4, v144
	v_lshl_add_u32 v2, v0, 10, v140
	v_lshl_add_u64 v[0:1], v[2:3], 1, s[64:65]
	s_waitcnt vmcnt(0)
	s_barrier
	global_load_dwordx2 v[132:133], v[0:1], off
	global_load_dwordx2 v[136:137], v[0:1], off offset:32
	global_load_dwordx2 v[146:147], v[0:1], off offset:256
	global_load_dwordx2 v[150:151], v[0:1], off offset:288
	v_add_u32_e32 v0, 0x4000, v2
	v_mov_b32_e32 v1, v3
	v_lshl_add_u64 v[0:1], v[0:1], 1, s[64:65]
	global_load_dwordx2 v[186:187], v[0:1], off
	global_load_dwordx2 v[190:191], v[0:1], off offset:32
	global_load_dwordx2 v[194:195], v[0:1], off offset:256
	global_load_dwordx2 v[198:199], v[0:1], off offset:288
	v_mov_b32_e32 v134, v3
	v_mov_b32_e32 v135, v3
	v_mov_b32_e32 v138, v3
	v_mov_b32_e32 v139, v3
	v_mov_b32_e32 v148, v3
	v_mov_b32_e32 v149, v3
	v_mov_b32_e32 v152, v3
	v_mov_b32_e32 v153, v3
	v_mov_b32_e32 v188, v3
	v_mov_b32_e32 v189, v3
	v_mov_b32_e32 v192, v3
	v_mov_b32_e32 v193, v3
	v_mov_b32_e32 v196, v3
	v_mov_b32_e32 v197, v3
	v_mov_b32_e32 v200, v3
	v_mov_b32_e32 v201, v3
	s_mov_b32 s4, 0x3fd744fd
	v_and_b32_e32 v141, 63, v145
	v_cmp_gt_u32_e32 vcc, 16, v141
	v_add_u32_e32 v0, 0x8000, v2
	v_mov_b32_e32 v1, v3
	v_lshl_add_u64 v[0:1], v[0:1], 1, s[64:65]
	global_load_dwordx2 v[202:203], v[0:1], off
	global_load_dwordx2 v[204:205], v[0:1], off offset:32
	global_load_dwordx2 v[206:207], v[0:1], off offset:256
	global_load_dwordx2 v[208:209], v[0:1], off offset:288
	v_add_u32_e32 v0, 0xc000, v2
	v_mov_b32_e32 v1, v3
	v_lshl_add_u64 v[0:1], v[0:1], 1, s[64:65]
	global_load_dwordx2 v[210:211], v[0:1], off
	global_load_dwordx2 v[212:213], v[0:1], off offset:32
	global_load_dwordx2 v[214:215], v[0:1], off offset:256
	global_load_dwordx2 v[216:217], v[0:1], off offset:288
	v_add_u32_e32 v0, 0x20000, v2
	v_mov_b32_e32 v1, v3
	v_lshl_add_u64 v[0:1], v[0:1], 1, s[64:65]
	global_load_dwordx2 v[220:221], v[0:1], off
	global_load_dwordx2 v[222:223], v[0:1], off offset:32
	global_load_dwordx2 v[224:225], v[0:1], off offset:256
	global_load_dwordx2 v[218:219], v[0:1], off offset:288
	v_add_u32_e32 v0, 0x24000, v2
	v_mov_b32_e32 v1, v3
	v_lshl_add_u64 v[0:1], v[0:1], 1, s[64:65]
	global_load_dwordx2 v[226:227], v[0:1], off
	global_load_dwordx2 v[228:229], v[0:1], off offset:32
	global_load_dwordx2 v[230:231], v[0:1], off offset:256
	global_load_dwordx2 v[232:233], v[0:1], off offset:288
	s_waitcnt vmcnt(16)
	s_nop 0
	v_cvt_f32_f16_e32 v0, v132
	v_cvt_f32_f16_sdwa v1, v132 dst_sel:DWORD dst_unused:UNUSED_PAD src0_sel:WORD_1
	v_cvt_f32_f16_e32 v132, v133
	v_cvt_f32_f16_sdwa v133, v133 dst_sel:DWORD dst_unused:UNUSED_PAD src0_sel:WORD_1
	v_mov_b32_e32 v134, v3
	v_pk_fma_f32 v[36:37], v[0:1], s[4:5], v[36:37] op_sel_hi:[1,0,1]
	v_cvt_f32_f16_e32 v0, v136
	v_pk_fma_f32 v[38:39], v[132:133], s[4:5], v[38:39] op_sel_hi:[1,0,1]
	v_cvt_f32_f16_sdwa v1, v136 dst_sel:DWORD dst_unused:UNUSED_PAD src0_sel:WORD_1
	v_cvt_f32_f16_e32 v132, v137
	v_cvt_f32_f16_sdwa v133, v137 dst_sel:DWORD dst_unused:UNUSED_PAD src0_sel:WORD_1
	v_mov_b32_e32 v135, v3
	v_pk_fma_f32 v[20:21], v[0:1], s[4:5], v[20:21] op_sel_hi:[1,0,1]
	v_cvt_f32_f16_e32 v0, v146
	v_pk_fma_f32 v[22:23], v[132:133], s[4:5], v[22:23] op_sel_hi:[1,0,1]
	v_cvt_f32_f16_sdwa v1, v146 dst_sel:DWORD dst_unused:UNUSED_PAD src0_sel:WORD_1
	v_cvt_f32_f16_e32 v132, v147
	v_cvt_f32_f16_sdwa v133, v147 dst_sel:DWORD dst_unused:UNUSED_PAD src0_sel:WORD_1
	v_mov_b32_e32 v138, v3
	v_pk_fma_f32 v[12:13], v[0:1], s[4:5], v[12:13] op_sel_hi:[1,0,1]
	v_cvt_f32_f16_e32 v0, v150
	v_pk_fma_f32 v[14:15], v[132:133], s[4:5], v[14:15] op_sel_hi:[1,0,1]
	v_cvt_f32_f16_sdwa v1, v150 dst_sel:DWORD dst_unused:UNUSED_PAD src0_sel:WORD_1
	v_cvt_f32_f16_e32 v132, v151
	v_cvt_f32_f16_sdwa v133, v151 dst_sel:DWORD dst_unused:UNUSED_PAD src0_sel:WORD_1
	v_mov_b32_e32 v139, v3
	v_pk_fma_f32 v[4:5], v[0:1], s[4:5], v[4:5] op_sel_hi:[1,0,1]
	v_cvt_f32_f16_e32 v0, v186
	v_pk_fma_f32 v[6:7], v[132:133], s[4:5], v[6:7] op_sel_hi:[1,0,1]
	v_cvt_f32_f16_sdwa v1, v186 dst_sel:DWORD dst_unused:UNUSED_PAD src0_sel:WORD_1
	v_cvt_f32_f16_e32 v132, v187
	v_cvt_f32_f16_sdwa v133, v187 dst_sel:DWORD dst_unused:UNUSED_PAD src0_sel:WORD_1
	v_pk_fma_f32 v[40:41], v[0:1], s[4:5], v[40:41] op_sel_hi:[1,0,1]
	v_cvt_f32_f16_e32 v0, v190
	v_pk_fma_f32 v[42:43], v[132:133], s[4:5], v[42:43] op_sel_hi:[1,0,1]
	v_cvt_f32_f16_sdwa v1, v190 dst_sel:DWORD dst_unused:UNUSED_PAD src0_sel:WORD_1
	v_cvt_f32_f16_e32 v132, v191
	v_cvt_f32_f16_sdwa v133, v191 dst_sel:DWORD dst_unused:UNUSED_PAD src0_sel:WORD_1
	v_mov_b32_e32 v148, v3
	v_pk_fma_f32 v[24:25], v[0:1], s[4:5], v[24:25] op_sel_hi:[1,0,1]
	v_cvt_f32_f16_e32 v0, v194
	v_pk_fma_f32 v[26:27], v[132:133], s[4:5], v[26:27] op_sel_hi:[1,0,1]
	v_cvt_f32_f16_sdwa v1, v194 dst_sel:DWORD dst_unused:UNUSED_PAD src0_sel:WORD_1
	v_cvt_f32_f16_e32 v132, v195
	v_cvt_f32_f16_sdwa v133, v195 dst_sel:DWORD dst_unused:UNUSED_PAD src0_sel:WORD_1
	v_mov_b32_e32 v149, v3
	v_pk_fma_f32 v[16:17], v[0:1], s[4:5], v[16:17] op_sel_hi:[1,0,1]
	v_cvt_f32_f16_e32 v0, v198
	v_pk_fma_f32 v[18:19], v[132:133], s[4:5], v[18:19] op_sel_hi:[1,0,1]
	v_cvt_f32_f16_sdwa v1, v198 dst_sel:DWORD dst_unused:UNUSED_PAD src0_sel:WORD_1
	v_cvt_f32_f16_e32 v132, v199
	v_cvt_f32_f16_sdwa v133, v199 dst_sel:DWORD dst_unused:UNUSED_PAD src0_sel:WORD_1
	v_mov_b32_e32 v152, v3
	v_pk_fma_f32 v[8:9], v[0:1], s[4:5], v[8:9] op_sel_hi:[1,0,1]
	v_pk_fma_f32 v[10:11], v[132:133], s[4:5], v[10:11] op_sel_hi:[1,0,1]
	v_mov_b32_e32 v153, v3
	v_mov_b32_e32 v188, v3
	v_mov_b32_e32 v189, v3
	v_mov_b32_e32 v192, v3
	v_mov_b32_e32 v193, v3
	v_mov_b32_e32 v196, v3
	v_mov_b32_e32 v197, v3
	v_mov_b32_e32 v200, v3
	v_mov_b32_e32 v201, v3
	s_waitcnt vmcnt(8)
	s_nop 0
	v_cvt_f32_f16_e32 v0, v202
	v_cvt_f32_f16_sdwa v1, v202 dst_sel:DWORD dst_unused:UNUSED_PAD src0_sel:WORD_1
	v_cvt_f32_f16_e32 v202, v203
	v_cvt_f32_f16_sdwa v203, v203 dst_sel:DWORD dst_unused:UNUSED_PAD src0_sel:WORD_1
	v_mov_b32_e32 v138, v3
	v_pk_fma_f32 v[100:101], v[0:1], s[4:5], v[100:101] op_sel_hi:[1,0,1]
	v_cvt_f32_f16_e32 v0, v204
	v_pk_fma_f32 v[102:103], v[202:203], s[4:5], v[102:103] op_sel_hi:[1,0,1]
	v_cvt_f32_f16_sdwa v1, v204 dst_sel:DWORD dst_unused:UNUSED_PAD src0_sel:WORD_1
	v_cvt_f32_f16_e32 v202, v205
	v_cvt_f32_f16_sdwa v203, v205 dst_sel:DWORD dst_unused:UNUSED_PAD src0_sel:WORD_1
	v_mov_b32_e32 v139, v3
	v_pk_fma_f32 v[84:85], v[0:1], s[4:5], v[84:85] op_sel_hi:[1,0,1]
	v_cvt_f32_f16_e32 v0, v206
	v_pk_fma_f32 v[86:87], v[202:203], s[4:5], v[86:87] op_sel_hi:[1,0,1]
	v_cvt_f32_f16_sdwa v1, v206 dst_sel:DWORD dst_unused:UNUSED_PAD src0_sel:WORD_1
	v_cvt_f32_f16_e32 v202, v207
	v_cvt_f32_f16_sdwa v203, v207 dst_sel:DWORD dst_unused:UNUSED_PAD src0_sel:WORD_1
	v_mov_b32_e32 v148, v3
	v_pk_fma_f32 v[64:65], v[0:1], s[4:5], v[64:65] op_sel_hi:[1,0,1]
	v_cvt_f32_f16_e32 v0, v208
	v_pk_fma_f32 v[66:67], v[202:203], s[4:5], v[66:67] op_sel_hi:[1,0,1]
	v_cvt_f32_f16_sdwa v1, v208 dst_sel:DWORD dst_unused:UNUSED_PAD src0_sel:WORD_1
	v_cvt_f32_f16_e32 v202, v209
	v_cvt_f32_f16_sdwa v203, v209 dst_sel:DWORD dst_unused:UNUSED_PAD src0_sel:WORD_1
	v_mov_b32_e32 v149, v3
	v_pk_fma_f32 v[32:33], v[0:1], s[4:5], v[32:33] op_sel_hi:[1,0,1]
	v_cvt_f32_f16_e32 v0, v210
	v_pk_fma_f32 v[34:35], v[202:203], s[4:5], v[34:35] op_sel_hi:[1,0,1]
	v_cvt_f32_f16_sdwa v1, v210 dst_sel:DWORD dst_unused:UNUSED_PAD src0_sel:WORD_1
	v_cvt_f32_f16_e32 v202, v211
	v_cvt_f32_f16_sdwa v203, v211 dst_sel:DWORD dst_unused:UNUSED_PAD src0_sel:WORD_1
	v_pk_fma_f32 v[104:105], v[0:1], s[4:5], v[104:105] op_sel_hi:[1,0,1]
	v_cvt_f32_f16_e32 v0, v212
	v_pk_fma_f32 v[106:107], v[202:203], s[4:5], v[106:107] op_sel_hi:[1,0,1]
	v_cvt_f32_f16_sdwa v1, v212 dst_sel:DWORD dst_unused:UNUSED_PAD src0_sel:WORD_1
	v_cvt_f32_f16_e32 v202, v213
	v_cvt_f32_f16_sdwa v203, v213 dst_sel:DWORD dst_unused:UNUSED_PAD src0_sel:WORD_1
	v_mov_b32_e32 v152, v3
	v_pk_fma_f32 v[88:89], v[0:1], s[4:5], v[88:89] op_sel_hi:[1,0,1]
	v_cvt_f32_f16_e32 v0, v214
	v_pk_fma_f32 v[90:91], v[202:203], s[4:5], v[90:91] op_sel_hi:[1,0,1]
	v_cvt_f32_f16_sdwa v1, v214 dst_sel:DWORD dst_unused:UNUSED_PAD src0_sel:WORD_1
	v_cvt_f32_f16_e32 v202, v215
	v_cvt_f32_f16_sdwa v203, v215 dst_sel:DWORD dst_unused:UNUSED_PAD src0_sel:WORD_1
	v_mov_b32_e32 v153, v3
	v_pk_fma_f32 v[68:69], v[0:1], s[4:5], v[68:69] op_sel_hi:[1,0,1]
	v_cvt_f32_f16_e32 v0, v216
	v_pk_fma_f32 v[70:71], v[202:203], s[4:5], v[70:71] op_sel_hi:[1,0,1]
	v_cvt_f32_f16_sdwa v1, v216 dst_sel:DWORD dst_unused:UNUSED_PAD src0_sel:WORD_1
	v_cvt_f32_f16_e32 v202, v217
	v_cvt_f32_f16_sdwa v203, v217 dst_sel:DWORD dst_unused:UNUSED_PAD src0_sel:WORD_1
	v_mov_b32_e32 v134, v3
	v_pk_fma_f32 v[28:29], v[0:1], s[4:5], v[28:29] op_sel_hi:[1,0,1]
	v_pk_fma_f32 v[30:31], v[202:203], s[4:5], v[30:31] op_sel_hi:[1,0,1]
	v_mov_b32_e32 v135, v3
	v_mov_b32_e32 v188, v3
	v_mov_b32_e32 v189, v3
	v_mov_b32_e32 v192, v3
	v_mov_b32_e32 v193, v3
	v_mov_b32_e32 v196, v3
	v_mov_b32_e32 v197, v3
	v_mov_b32_e32 v200, v3
	v_mov_b32_e32 v201, v3
	s_waitcnt vmcnt(0)
	s_nop 0
	v_cvt_f32_f16_e32 v0, v220
	v_cvt_f32_f16_sdwa v1, v220 dst_sel:DWORD dst_unused:UNUSED_PAD src0_sel:WORD_1
	v_cvt_f32_f16_e32 v134, v221
	v_cvt_f32_f16_sdwa v135, v221 dst_sel:DWORD dst_unused:UNUSED_PAD src0_sel:WORD_1
	v_mov_b32_e32 v148, v3
	v_pk_fma_f32 v[128:129], v[0:1], s[4:5], v[128:129] op_sel_hi:[1,0,1]
	v_cvt_f32_f16_e32 v0, v222
	v_cvt_f32_f16_sdwa v1, v222 dst_sel:DWORD dst_unused:UNUSED_PAD src0_sel:WORD_1
	v_pk_fma_f32 v[130:131], v[134:135], s[4:5], v[130:131] op_sel_hi:[1,0,1]
	v_cvt_f32_f16_e32 v134, v223
	v_cvt_f32_f16_sdwa v135, v223 dst_sel:DWORD dst_unused:UNUSED_PAD src0_sel:WORD_1
	v_pk_fma_f32 v[124:125], v[0:1], s[4:5], v[124:125] op_sel_hi:[1,0,1]
	v_cvt_f32_f16_e32 v0, v224
	v_cvt_f32_f16_sdwa v1, v224 dst_sel:DWORD dst_unused:UNUSED_PAD src0_sel:WORD_1
	v_pk_fma_f32 v[126:127], v[134:135], s[4:5], v[126:127] op_sel_hi:[1,0,1]
	v_cvt_f32_f16_e32 v134, v225
	v_cvt_f32_f16_sdwa v135, v225 dst_sel:DWORD dst_unused:UNUSED_PAD src0_sel:WORD_1
	v_pk_fma_f32 v[108:109], v[0:1], s[4:5], v[108:109] op_sel_hi:[1,0,1]
	v_cvt_f32_f16_e32 v0, v218
	v_cvt_f32_f16_sdwa v1, v218 dst_sel:DWORD dst_unused:UNUSED_PAD src0_sel:WORD_1
	v_cvt_f32_f16_e32 v218, v219
	v_cvt_f32_f16_sdwa v219, v219 dst_sel:DWORD dst_unused:UNUSED_PAD src0_sel:WORD_1
	v_pk_fma_f32 v[110:111], v[134:135], s[4:5], v[110:111] op_sel_hi:[1,0,1]
	v_pk_fma_f32 v[92:93], v[0:1], s[4:5], v[92:93] op_sel_hi:[1,0,1]
	v_cvt_f32_f16_e32 v0, v226
	v_pk_fma_f32 v[94:95], v[218:219], s[4:5], v[94:95] op_sel_hi:[1,0,1]
	v_cvt_f32_f16_sdwa v1, v226 dst_sel:DWORD dst_unused:UNUSED_PAD src0_sel:WORD_1
	v_cvt_f32_f16_e32 v218, v227
	v_cvt_f32_f16_sdwa v219, v227 dst_sel:DWORD dst_unused:UNUSED_PAD src0_sel:WORD_1
	v_pk_fma_f32 v[120:121], v[0:1], s[4:5], v[120:121] op_sel_hi:[1,0,1]
	v_cvt_f32_f16_e32 v0, v228
	v_pk_fma_f32 v[122:123], v[218:219], s[4:5], v[122:123] op_sel_hi:[1,0,1]
	v_cvt_f32_f16_sdwa v1, v228 dst_sel:DWORD dst_unused:UNUSED_PAD src0_sel:WORD_1
	v_cvt_f32_f16_e32 v218, v229
	v_cvt_f32_f16_sdwa v219, v229 dst_sel:DWORD dst_unused:UNUSED_PAD src0_sel:WORD_1
	v_mov_b32_e32 v149, v3
	v_pk_fma_f32 v[116:117], v[0:1], s[4:5], v[116:117] op_sel_hi:[1,0,1]
	v_cvt_f32_f16_e32 v0, v230
	v_pk_fma_f32 v[118:119], v[218:219], s[4:5], v[118:119] op_sel_hi:[1,0,1]
	v_cvt_f32_f16_sdwa v1, v230 dst_sel:DWORD dst_unused:UNUSED_PAD src0_sel:WORD_1
	v_cvt_f32_f16_e32 v218, v231
	v_cvt_f32_f16_sdwa v219, v231 dst_sel:DWORD dst_unused:UNUSED_PAD src0_sel:WORD_1
	v_mov_b32_e32 v138, v3
	v_pk_fma_f32 v[112:113], v[0:1], s[4:5], v[112:113] op_sel_hi:[1,0,1]
	v_cvt_f32_f16_e32 v0, v232
	v_pk_fma_f32 v[114:115], v[218:219], s[4:5], v[114:115] op_sel_hi:[1,0,1]
	v_cvt_f32_f16_sdwa v1, v232 dst_sel:DWORD dst_unused:UNUSED_PAD src0_sel:WORD_1
	v_cvt_f32_f16_e32 v218, v233
	v_cvt_f32_f16_sdwa v219, v233 dst_sel:DWORD dst_unused:UNUSED_PAD src0_sel:WORD_1
	v_mov_b32_e32 v139, v3
	v_pk_fma_f32 v[96:97], v[0:1], s[4:5], v[96:97] op_sel_hi:[1,0,1]
	v_add_u32_e32 v0, 0x28000, v2
	v_pk_fma_f32 v[98:99], v[218:219], s[4:5], v[98:99] op_sel_hi:[1,0,1]
	v_mov_b32_e32 v1, v3
	v_add_u32_e32 v2, 0x2c000, v2
	v_lshl_add_u64 v[132:133], v[0:1], 1, s[64:65]
	v_lshl_add_u64 v[134:135], v[2:3], 1, s[64:65]
	global_load_dwordx2 v[0:1], v[132:133], off
	global_load_dwordx2 v[146:147], v[132:133], off offset:32
	global_load_dwordx2 v[136:137], v[132:133], off offset:256
	s_nop 0
	global_load_dwordx2 v[132:133], v[132:133], off offset:288
	s_nop 0
	global_load_dwordx2 v[150:151], v[134:135], off
	global_load_dwordx2 v[186:187], v[134:135], off offset:32
	global_load_dwordx2 v[190:191], v[134:135], off offset:256
	global_load_dwordx2 v[194:195], v[134:135], off offset:288
	v_mov_b32_e32 v2, v3
	v_mov_b32_e32 v134, v3
	v_mov_b32_e32 v135, v3
	v_mov_b32_e32 v152, v3
	v_mov_b32_e32 v153, v3
	v_mov_b32_e32 v188, v3
	v_mov_b32_e32 v189, v3
	v_mov_b32_e32 v192, v3
	v_mov_b32_e32 v193, v3
	v_mov_b32_e32 v196, v3
	v_mov_b32_e32 v197, v3
	s_waitcnt vmcnt(7)
	v_mov_b64_e32 v[200:201], v[2:3]
	v_mov_b64_e32 v[198:199], v[0:1]
	s_waitcnt vmcnt(0)
	s_nop 0
	v_cvt_f32_f16_e32 v0, v198
	v_cvt_f32_f16_sdwa v1, v198 dst_sel:DWORD dst_unused:UNUSED_PAD src0_sel:WORD_1
	v_cvt_f32_f16_e32 v134, v199
	v_cvt_f32_f16_sdwa v135, v199 dst_sel:DWORD dst_unused:UNUSED_PAD src0_sel:WORD_1
	v_pk_fma_f32 v[80:81], v[0:1], s[4:5], v[80:81] op_sel_hi:[1,0,1]
	v_cvt_f32_f16_e32 v0, v146
	v_cvt_f32_f16_sdwa v1, v146 dst_sel:DWORD dst_unused:UNUSED_PAD src0_sel:WORD_1
	v_pk_fma_f32 v[82:83], v[134:135], s[4:5], v[82:83] op_sel_hi:[1,0,1]
	v_cvt_f32_f16_e32 v134, v147
	v_cvt_f32_f16_sdwa v135, v147 dst_sel:DWORD dst_unused:UNUSED_PAD src0_sel:WORD_1
	v_pk_fma_f32 v[76:77], v[0:1], s[4:5], v[76:77] op_sel_hi:[1,0,1]
	v_cvt_f32_f16_e32 v0, v136
	v_cvt_f32_f16_sdwa v1, v136 dst_sel:DWORD dst_unused:UNUSED_PAD src0_sel:WORD_1
	v_pk_fma_f32 v[78:79], v[134:135], s[4:5], v[78:79] op_sel_hi:[1,0,1]
	v_cvt_f32_f16_e32 v134, v137
	v_cvt_f32_f16_sdwa v135, v137 dst_sel:DWORD dst_unused:UNUSED_PAD src0_sel:WORD_1
	v_pk_fma_f32 v[56:57], v[0:1], s[4:5], v[56:57] op_sel_hi:[1,0,1]
	v_cvt_f32_f16_e32 v0, v132
	v_cvt_f32_f16_sdwa v1, v132 dst_sel:DWORD dst_unused:UNUSED_PAD src0_sel:WORD_1
	v_cvt_f32_f16_e32 v132, v133
	v_cvt_f32_f16_sdwa v133, v133 dst_sel:DWORD dst_unused:UNUSED_PAD src0_sel:WORD_1
	v_pk_fma_f32 v[58:59], v[134:135], s[4:5], v[58:59] op_sel_hi:[1,0,1]
	v_pk_fma_f32 v[52:53], v[0:1], s[4:5], v[52:53] op_sel_hi:[1,0,1]
	v_cvt_f32_f16_e32 v0, v150
	v_pk_fma_f32 v[54:55], v[132:133], s[4:5], v[54:55] op_sel_hi:[1,0,1]
	v_cvt_f32_f16_sdwa v1, v150 dst_sel:DWORD dst_unused:UNUSED_PAD src0_sel:WORD_1
	v_cvt_f32_f16_e32 v132, v151
	v_cvt_f32_f16_sdwa v133, v151 dst_sel:DWORD dst_unused:UNUSED_PAD src0_sel:WORD_1
	v_mov_b32_e32 v134, v20
	v_pk_fma_f32 v[72:73], v[0:1], s[4:5], v[72:73] op_sel_hi:[1,0,1]
	v_cvt_f32_f16_e32 v0, v186
	v_pk_fma_f32 v[74:75], v[132:133], s[4:5], v[74:75] op_sel_hi:[1,0,1]
	v_cvt_f32_f16_sdwa v1, v186 dst_sel:DWORD dst_unused:UNUSED_PAD src0_sel:WORD_1
	v_cvt_f32_f16_e32 v132, v187
	v_cvt_f32_f16_sdwa v133, v187 dst_sel:DWORD dst_unused:UNUSED_PAD src0_sel:WORD_1
	v_mov_b32_e32 v135, v23
	v_pk_fma_f32 v[60:61], v[0:1], s[4:5], v[60:61] op_sel_hi:[1,0,1]
	v_cvt_f32_f16_e32 v0, v190
	v_pk_fma_f32 v[62:63], v[132:133], s[4:5], v[62:63] op_sel_hi:[1,0,1]
	v_cvt_f32_f16_sdwa v1, v190 dst_sel:DWORD dst_unused:UNUSED_PAD src0_sel:WORD_1
	v_cvt_f32_f16_e32 v132, v191
	v_cvt_f32_f16_sdwa v133, v191 dst_sel:DWORD dst_unused:UNUSED_PAD src0_sel:WORD_1
	v_add_f32_e32 v137, v14, v15
	v_pk_fma_f32 v[48:49], v[0:1], s[4:5], v[48:49] op_sel_hi:[1,0,1]
	v_cvt_f32_f16_e32 v0, v194
	v_pk_fma_f32 v[50:51], v[132:133], s[4:5], v[50:51] op_sel_hi:[1,0,1]
	v_cvt_f32_f16_sdwa v1, v194 dst_sel:DWORD dst_unused:UNUSED_PAD src0_sel:WORD_1
	v_cvt_f32_f16_e32 v132, v195
	v_cvt_f32_f16_sdwa v133, v195 dst_sel:DWORD dst_unused:UNUSED_PAD src0_sel:WORD_1
	v_mov_b32_e32 v136, v5
	v_pk_fma_f32 v[44:45], v[0:1], s[4:5], v[44:45] op_sel_hi:[1,0,1]
	v_mov_b32_e32 v0, v37
	v_pk_fma_f32 v[46:47], v[132:133], s[4:5], v[46:47] op_sel_hi:[1,0,1]
	v_mov_b32_e32 v1, v38
	v_mov_b32_e32 v132, v36
	v_mov_b32_e32 v133, v39
	v_pk_add_f32 v[0:1], v[0:1], v[132:133]
	v_mov_b32_e32 v132, v21
	v_mov_b32_e32 v133, v22
	v_pk_add_f32 v[132:133], v[132:133], v[134:135]
	v_add_f32_e32 v0, v0, v1
	v_pk_add_f32 v[132:133], v[132:133], v[132:133] op_sel_hi:[0,1]
	v_add_f32_e32 v1, 0, v0
	v_add_f32_e32 v135, v12, v13
	v_mov_b32_e32 v134, v4
	v_mov_b32_e32 v132, v6
	v_mov_b32_e32 v0, v7
	v_pk_add_f32 v[134:135], v[134:135], v[136:137]
	v_pk_add_f32 v[0:1], v[132:133], v[0:1]
	s_lshl_b32 s4, s8, 3
	v_pk_add_f32 v[0:1], v[134:135], v[0:1]
	s_add_i32 s7, s4, 0
	v_add_f32_e32 v0, v0, v1
	ds_bpermute_b32 v1, v183, v0
	s_waitcnt lgkmcnt(0)
	v_add_f32_e32 v0, v0, v1
	ds_bpermute_b32 v1, v184, v0
	s_waitcnt lgkmcnt(0)
	v_add_f32_e32 v0, v0, v1
	v_fmamk_f32 v2, v0, 0xbc800000, v39
	v_fmamk_f32 v133, v0, 0xbc800000, v37
	v_fmamk_f32 v1, v0, 0xbc800000, v38
	v_fmamk_f32 v132, v0, 0xbc800000, v36
	v_mul_f32_e32 v133, v133, v133
	v_mul_f32_e32 v2, v2, v2
	v_fmac_f32_e32 v133, v132, v132
	v_fmac_f32_e32 v2, v1, v1
	v_fmamk_f32 v132, v0, 0xbc800000, v23
	v_fmamk_f32 v134, v0, 0xbc800000, v21
	v_add_f32_e32 v1, v133, v2
	v_fmamk_f32 v2, v0, 0xbc800000, v22
	v_fmamk_f32 v133, v0, 0xbc800000, v20
	v_mul_f32_e32 v134, v134, v134
	v_mul_f32_e32 v132, v132, v132
	v_fmac_f32_e32 v134, v133, v133
	v_fmac_f32_e32 v132, v2, v2
	v_add_f32_e32 v2, v134, v132
	v_fmamk_f32 v132, v0, 0xbc800000, v15
	v_fmamk_f32 v134, v0, 0xbc800000, v13
	v_add_f32_e32 v1, v1, v2
	v_fmamk_f32 v2, v0, 0xbc800000, v14
	v_fmamk_f32 v133, v0, 0xbc800000, v12
	v_mul_f32_e32 v134, v134, v134
	v_mul_f32_e32 v132, v132, v132
	v_fmac_f32_e32 v134, v133, v133
	v_fmac_f32_e32 v132, v2, v2
	v_add_f32_e32 v2, v134, v132
	v_fmamk_f32 v132, v0, 0xbc800000, v7
	v_fmamk_f32 v134, v0, 0xbc800000, v5
	v_add_f32_e32 v1, v2, v1
	v_fmamk_f32 v2, v0, 0xbc800000, v6
	v_fmamk_f32 v133, v0, 0xbc800000, v4
	v_mul_f32_e32 v134, v134, v134
	v_mul_f32_e32 v132, v132, v132
	v_fmac_f32_e32 v134, v133, v133
	v_fmac_f32_e32 v132, v2, v2
	v_add_f32_e32 v2, v134, v132
	v_add_f32_e32 v1, v2, v1
	ds_bpermute_b32 v2, v183, v1
	s_waitcnt lgkmcnt(0)
	v_add_f32_e32 v1, v1, v2
	ds_bpermute_b32 v2, v184, v1
	s_and_saveexec_b64 s[4:5], vcc
	s_cbranch_execz .LBB0_1156
	s_lshl_b32 s8, s0, 11
	s_add_i32 s8, s7, s8
	v_mul_f32_e32 v0, 0x3c800000, v0
	s_waitcnt lgkmcnt(0)
	v_add_f32_e32 v1, v1, v2
	v_lshl_add_u32 v2, v144, 5, s8
	ds_write_b64 v2, v[0:1]

.LBB0_1210:
	s_lshl_b32 s4, s8, 5
	s_lshl_b32 s5, s44, 8
	s_or_b32 s4, s5, s4
	v_lshrrev_b32_e32 v0, 2, v145
	s_lshl_b32 s6, s1, 8
	v_and_or_b32 v140, v0, 12, s4
	s_add_i32 s4, s6, s14
	v_or_b32_e32 v0, s4, v144
	v_lshl_add_u32 v2, v0, 10, v140
	v_lshl_add_u64 v[0:1], v[2:3], 1, s[64:65]
	s_waitcnt vmcnt(0)
	s_barrier
	global_load_dwordx2 v[132:133], v[0:1], off
	global_load_dwordx2 v[136:137], v[0:1], off offset:32
	global_load_dwordx2 v[146:147], v[0:1], off offset:256
	global_load_dwordx2 v[150:151], v[0:1], off offset:288
	v_add_u32_e32 v0, 0x4000, v2
	v_mov_b32_e32 v1, v3
	v_lshl_add_u64 v[0:1], v[0:1], 1, s[64:65]
	global_load_dwordx2 v[186:187], v[0:1], off
	global_load_dwordx2 v[190:191], v[0:1], off offset:32
	global_load_dwordx2 v[194:195], v[0:1], off offset:256
	global_load_dwordx2 v[198:199], v[0:1], off offset:288
	v_mov_b32_e32 v134, v3
	v_mov_b32_e32 v135, v3
	v_mov_b32_e32 v138, v3
	v_mov_b32_e32 v139, v3
	v_mov_b32_e32 v148, v3
	v_mov_b32_e32 v149, v3
	v_mov_b32_e32 v152, v3
	v_mov_b32_e32 v153, v3
	v_mov_b32_e32 v188, v3
	v_mov_b32_e32 v189, v3
	v_mov_b32_e32 v192, v3
	v_mov_b32_e32 v193, v3
	v_mov_b32_e32 v196, v3
	v_mov_b32_e32 v197, v3
	v_mov_b32_e32 v200, v3
	v_mov_b32_e32 v201, v3
	s_mov_b32 s4, 0x3fd744fd
	v_and_b32_e32 v141, 63, v145
	v_cmp_gt_u32_e32 vcc, 16, v141
	v_add_u32_e32 v0, 0x8000, v2
	v_mov_b32_e32 v1, v3
	v_lshl_add_u64 v[0:1], v[0:1], 1, s[64:65]
	global_load_dwordx2 v[202:203], v[0:1], off
	global_load_dwordx2 v[204:205], v[0:1], off offset:32
	global_load_dwordx2 v[206:207], v[0:1], off offset:256
	global_load_dwordx2 v[208:209], v[0:1], off offset:288
	v_add_u32_e32 v0, 0xc000, v2
	v_mov_b32_e32 v1, v3
	v_lshl_add_u64 v[0:1], v[0:1], 1, s[64:65]
	global_load_dwordx2 v[210:211], v[0:1], off
	global_load_dwordx2 v[212:213], v[0:1], off offset:32
	global_load_dwordx2 v[214:215], v[0:1], off offset:256
	global_load_dwordx2 v[216:217], v[0:1], off offset:288
	v_add_u32_e32 v0, 0x20000, v2
	v_mov_b32_e32 v1, v3
	v_lshl_add_u64 v[0:1], v[0:1], 1, s[64:65]
	global_load_dwordx2 v[220:221], v[0:1], off
	global_load_dwordx2 v[222:223], v[0:1], off offset:32
	global_load_dwordx2 v[224:225], v[0:1], off offset:256
	global_load_dwordx2 v[218:219], v[0:1], off offset:288
	v_add_u32_e32 v0, 0x24000, v2
	v_mov_b32_e32 v1, v3
	v_lshl_add_u64 v[0:1], v[0:1], 1, s[64:65]
	global_load_dwordx2 v[226:227], v[0:1], off
	global_load_dwordx2 v[228:229], v[0:1], off offset:32
	global_load_dwordx2 v[230:231], v[0:1], off offset:256
	global_load_dwordx2 v[232:233], v[0:1], off offset:288
	s_waitcnt vmcnt(16)
	s_nop 0
	v_cvt_f32_f16_e32 v0, v132
	v_cvt_f32_f16_sdwa v1, v132 dst_sel:DWORD dst_unused:UNUSED_PAD src0_sel:WORD_1
	v_cvt_f32_f16_e32 v132, v133
	v_cvt_f32_f16_sdwa v133, v133 dst_sel:DWORD dst_unused:UNUSED_PAD src0_sel:WORD_1
	v_mov_b32_e32 v134, v3
	v_pk_fma_f32 v[36:37], v[0:1], s[4:5], v[36:37] op_sel_hi:[1,0,1]
	v_cvt_f32_f16_e32 v0, v136
	v_pk_fma_f32 v[38:39], v[132:133], s[4:5], v[38:39] op_sel_hi:[1,0,1]
	v_cvt_f32_f16_sdwa v1, v136 dst_sel:DWORD dst_unused:UNUSED_PAD src0_sel:WORD_1
	v_cvt_f32_f16_e32 v132, v137
	v_cvt_f32_f16_sdwa v133, v137 dst_sel:DWORD dst_unused:UNUSED_PAD src0_sel:WORD_1
	v_mov_b32_e32 v135, v3
	v_pk_fma_f32 v[24:25], v[0:1], s[4:5], v[24:25] op_sel_hi:[1,0,1]
	v_cvt_f32_f16_e32 v0, v146
	v_pk_fma_f32 v[26:27], v[132:133], s[4:5], v[26:27] op_sel_hi:[1,0,1]
	v_cvt_f32_f16_sdwa v1, v146 dst_sel:DWORD dst_unused:UNUSED_PAD src0_sel:WORD_1
	v_cvt_f32_f16_e32 v132, v147
	v_cvt_f32_f16_sdwa v133, v147 dst_sel:DWORD dst_unused:UNUSED_PAD src0_sel:WORD_1
	v_mov_b32_e32 v138, v3
	v_pk_fma_f32 v[16:17], v[0:1], s[4:5], v[16:17] op_sel_hi:[1,0,1]
	v_cvt_f32_f16_e32 v0, v150
	v_pk_fma_f32 v[18:19], v[132:133], s[4:5], v[18:19] op_sel_hi:[1,0,1]
	v_cvt_f32_f16_sdwa v1, v150 dst_sel:DWORD dst_unused:UNUSED_PAD src0_sel:WORD_1
	v_cvt_f32_f16_e32 v132, v151
	v_cvt_f32_f16_sdwa v133, v151 dst_sel:DWORD dst_unused:UNUSED_PAD src0_sel:WORD_1
	v_mov_b32_e32 v139, v3
	v_pk_fma_f32 v[8:9], v[0:1], s[4:5], v[8:9] op_sel_hi:[1,0,1]
	v_cvt_f32_f16_e32 v0, v186
	v_pk_fma_f32 v[10:11], v[132:133], s[4:5], v[10:11] op_sel_hi:[1,0,1]
	v_cvt_f32_f16_sdwa v1, v186 dst_sel:DWORD dst_unused:UNUSED_PAD src0_sel:WORD_1
	v_cvt_f32_f16_e32 v132, v187
	v_cvt_f32_f16_sdwa v133, v187 dst_sel:DWORD dst_unused:UNUSED_PAD src0_sel:WORD_1
	v_pk_fma_f32 v[40:41], v[0:1], s[4:5], v[40:41] op_sel_hi:[1,0,1]
	v_cvt_f32_f16_e32 v0, v190
	v_pk_fma_f32 v[42:43], v[132:133], s[4:5], v[42:43] op_sel_hi:[1,0,1]
	v_cvt_f32_f16_sdwa v1, v190 dst_sel:DWORD dst_unused:UNUSED_PAD src0_sel:WORD_1
	v_cvt_f32_f16_e32 v132, v191
	v_cvt_f32_f16_sdwa v133, v191 dst_sel:DWORD dst_unused:UNUSED_PAD src0_sel:WORD_1
	v_mov_b32_e32 v148, v3
	v_pk_fma_f32 v[20:21], v[0:1], s[4:5], v[20:21] op_sel_hi:[1,0,1]
	v_cvt_f32_f16_e32 v0, v194
	v_pk_fma_f32 v[22:23], v[132:133], s[4:5], v[22:23] op_sel_hi:[1,0,1]
	v_cvt_f32_f16_sdwa v1, v194 dst_sel:DWORD dst_unused:UNUSED_PAD src0_sel:WORD_1
	v_cvt_f32_f16_e32 v132, v195
	v_cvt_f32_f16_sdwa v133, v195 dst_sel:DWORD dst_unused:UNUSED_PAD src0_sel:WORD_1
	v_mov_b32_e32 v149, v3
	v_pk_fma_f32 v[12:13], v[0:1], s[4:5], v[12:13] op_sel_hi:[1,0,1]
	v_cvt_f32_f16_e32 v0, v198
	v_pk_fma_f32 v[14:15], v[132:133], s[4:5], v[14:15] op_sel_hi:[1,0,1]
	v_cvt_f32_f16_sdwa v1, v198 dst_sel:DWORD dst_unused:UNUSED_PAD src0_sel:WORD_1
	v_cvt_f32_f16_e32 v132, v199
	v_cvt_f32_f16_sdwa v133, v199 dst_sel:DWORD dst_unused:UNUSED_PAD src0_sel:WORD_1
	v_mov_b32_e32 v152, v3
	v_pk_fma_f32 v[4:5], v[0:1], s[4:5], v[4:5] op_sel_hi:[1,0,1]
	v_pk_fma_f32 v[6:7], v[132:133], s[4:5], v[6:7] op_sel_hi:[1,0,1]
	v_mov_b32_e32 v153, v3
	v_mov_b32_e32 v188, v3
	v_mov_b32_e32 v189, v3
	v_mov_b32_e32 v192, v3
	v_mov_b32_e32 v193, v3
	v_mov_b32_e32 v196, v3
	v_mov_b32_e32 v197, v3
	v_mov_b32_e32 v200, v3
	v_mov_b32_e32 v201, v3
	s_waitcnt vmcnt(8)
	s_nop 0
	v_cvt_f32_f16_e32 v0, v202
	v_cvt_f32_f16_sdwa v1, v202 dst_sel:DWORD dst_unused:UNUSED_PAD src0_sel:WORD_1
	v_cvt_f32_f16_e32 v202, v203
	v_cvt_f32_f16_sdwa v203, v203 dst_sel:DWORD dst_unused:UNUSED_PAD src0_sel:WORD_1
	v_mov_b32_e32 v138, v3
	v_pk_fma_f32 v[100:101], v[0:1], s[4:5], v[100:101] op_sel_hi:[1,0,1]
	v_cvt_f32_f16_e32 v0, v204
	v_pk_fma_f32 v[102:103], v[202:203], s[4:5], v[102:103] op_sel_hi:[1,0,1]
	v_cvt_f32_f16_sdwa v1, v204 dst_sel:DWORD dst_unused:UNUSED_PAD src0_sel:WORD_1
	v_cvt_f32_f16_e32 v202, v205
	v_cvt_f32_f16_sdwa v203, v205 dst_sel:DWORD dst_unused:UNUSED_PAD src0_sel:WORD_1
	v_mov_b32_e32 v139, v3
	v_pk_fma_f32 v[88:89], v[0:1], s[4:5], v[88:89] op_sel_hi:[1,0,1]
	v_cvt_f32_f16_e32 v0, v206
	v_pk_fma_f32 v[90:91], v[202:203], s[4:5], v[90:91] op_sel_hi:[1,0,1]
	v_cvt_f32_f16_sdwa v1, v206 dst_sel:DWORD dst_unused:UNUSED_PAD src0_sel:WORD_1
	v_cvt_f32_f16_e32 v202, v207
	v_cvt_f32_f16_sdwa v203, v207 dst_sel:DWORD dst_unused:UNUSED_PAD src0_sel:WORD_1
	v_mov_b32_e32 v148, v3
	v_pk_fma_f32 v[52:53], v[0:1], s[4:5], v[52:53] op_sel_hi:[1,0,1]
	v_cvt_f32_f16_e32 v0, v208
	v_pk_fma_f32 v[54:55], v[202:203], s[4:5], v[54:55] op_sel_hi:[1,0,1]
	v_cvt_f32_f16_sdwa v1, v208 dst_sel:DWORD dst_unused:UNUSED_PAD src0_sel:WORD_1
	v_cvt_f32_f16_e32 v202, v209
	v_cvt_f32_f16_sdwa v203, v209 dst_sel:DWORD dst_unused:UNUSED_PAD src0_sel:WORD_1
	v_mov_b32_e32 v149, v3
	v_pk_fma_f32 v[32:33], v[0:1], s[4:5], v[32:33] op_sel_hi:[1,0,1]
	v_cvt_f32_f16_e32 v0, v210
	v_pk_fma_f32 v[34:35], v[202:203], s[4:5], v[34:35] op_sel_hi:[1,0,1]
	v_cvt_f32_f16_sdwa v1, v210 dst_sel:DWORD dst_unused:UNUSED_PAD src0_sel:WORD_1
	v_cvt_f32_f16_e32 v202, v211
	v_cvt_f32_f16_sdwa v203, v211 dst_sel:DWORD dst_unused:UNUSED_PAD src0_sel:WORD_1
	v_pk_fma_f32 v[104:105], v[0:1], s[4:5], v[104:105] op_sel_hi:[1,0,1]
	v_cvt_f32_f16_e32 v0, v212
	v_pk_fma_f32 v[106:107], v[202:203], s[4:5], v[106:107] op_sel_hi:[1,0,1]
	v_cvt_f32_f16_sdwa v1, v212 dst_sel:DWORD dst_unused:UNUSED_PAD src0_sel:WORD_1
	v_cvt_f32_f16_e32 v202, v213
	v_cvt_f32_f16_sdwa v203, v213 dst_sel:DWORD dst_unused:UNUSED_PAD src0_sel:WORD_1
	v_mov_b32_e32 v152, v3
	v_pk_fma_f32 v[84:85], v[0:1], s[4:5], v[84:85] op_sel_hi:[1,0,1]
	v_cvt_f32_f16_e32 v0, v214
	v_pk_fma_f32 v[86:87], v[202:203], s[4:5], v[86:87] op_sel_hi:[1,0,1]
	v_cvt_f32_f16_sdwa v1, v214 dst_sel:DWORD dst_unused:UNUSED_PAD src0_sel:WORD_1
	v_cvt_f32_f16_e32 v202, v215
	v_cvt_f32_f16_sdwa v203, v215 dst_sel:DWORD dst_unused:UNUSED_PAD src0_sel:WORD_1
	v_mov_b32_e32 v153, v3
	v_pk_fma_f32 v[48:49], v[0:1], s[4:5], v[48:49] op_sel_hi:[1,0,1]
	v_cvt_f32_f16_e32 v0, v216
	v_pk_fma_f32 v[50:51], v[202:203], s[4:5], v[50:51] op_sel_hi:[1,0,1]
	v_cvt_f32_f16_sdwa v1, v216 dst_sel:DWORD dst_unused:UNUSED_PAD src0_sel:WORD_1
	v_cvt_f32_f16_e32 v202, v217
	v_cvt_f32_f16_sdwa v203, v217 dst_sel:DWORD dst_unused:UNUSED_PAD src0_sel:WORD_1
	v_mov_b32_e32 v134, v3
	v_pk_fma_f32 v[28:29], v[0:1], s[4:5], v[28:29] op_sel_hi:[1,0,1]
	v_pk_fma_f32 v[30:31], v[202:203], s[4:5], v[30:31] op_sel_hi:[1,0,1]
	v_mov_b32_e32 v135, v3
	v_mov_b32_e32 v188, v3
	v_mov_b32_e32 v189, v3
	v_mov_b32_e32 v192, v3
	v_mov_b32_e32 v193, v3
	v_mov_b32_e32 v196, v3
	v_mov_b32_e32 v197, v3
	v_mov_b32_e32 v200, v3
	v_mov_b32_e32 v201, v3
	s_waitcnt vmcnt(0)
	s_nop 0
	v_cvt_f32_f16_e32 v0, v220
	v_cvt_f32_f16_sdwa v1, v220 dst_sel:DWORD dst_unused:UNUSED_PAD src0_sel:WORD_1
	v_cvt_f32_f16_e32 v134, v221
	v_cvt_f32_f16_sdwa v135, v221 dst_sel:DWORD dst_unused:UNUSED_PAD src0_sel:WORD_1
	v_mov_b32_e32 v148, v3
	v_pk_fma_f32 v[128:129], v[0:1], s[4:5], v[128:129] op_sel_hi:[1,0,1]
	v_cvt_f32_f16_e32 v0, v222
	v_cvt_f32_f16_sdwa v1, v222 dst_sel:DWORD dst_unused:UNUSED_PAD src0_sel:WORD_1
	v_pk_fma_f32 v[130:131], v[134:135], s[4:5], v[130:131] op_sel_hi:[1,0,1]
	v_cvt_f32_f16_e32 v134, v223
	v_cvt_f32_f16_sdwa v135, v223 dst_sel:DWORD dst_unused:UNUSED_PAD src0_sel:WORD_1
	v_pk_fma_f32 v[124:125], v[0:1], s[4:5], v[124:125] op_sel_hi:[1,0,1]
	v_cvt_f32_f16_e32 v0, v224
	v_cvt_f32_f16_sdwa v1, v224 dst_sel:DWORD dst_unused:UNUSED_PAD src0_sel:WORD_1
	v_pk_fma_f32 v[126:127], v[134:135], s[4:5], v[126:127] op_sel_hi:[1,0,1]
	v_cvt_f32_f16_e32 v134, v225
	v_cvt_f32_f16_sdwa v135, v225 dst_sel:DWORD dst_unused:UNUSED_PAD src0_sel:WORD_1
	v_pk_fma_f32 v[112:113], v[0:1], s[4:5], v[112:113] op_sel_hi:[1,0,1]
	v_cvt_f32_f16_e32 v0, v218
	v_cvt_f32_f16_sdwa v1, v218 dst_sel:DWORD dst_unused:UNUSED_PAD src0_sel:WORD_1
	v_cvt_f32_f16_e32 v218, v219
	v_cvt_f32_f16_sdwa v219, v219 dst_sel:DWORD dst_unused:UNUSED_PAD src0_sel:WORD_1
	v_pk_fma_f32 v[114:115], v[134:135], s[4:5], v[114:115] op_sel_hi:[1,0,1]
	v_pk_fma_f32 v[96:97], v[0:1], s[4:5], v[96:97] op_sel_hi:[1,0,1]
	v_cvt_f32_f16_e32 v0, v226
	v_pk_fma_f32 v[98:99], v[218:219], s[4:5], v[98:99] op_sel_hi:[1,0,1]
	v_cvt_f32_f16_sdwa v1, v226 dst_sel:DWORD dst_unused:UNUSED_PAD src0_sel:WORD_1
	v_cvt_f32_f16_e32 v218, v227
	v_cvt_f32_f16_sdwa v219, v227 dst_sel:DWORD dst_unused:UNUSED_PAD src0_sel:WORD_1
	v_pk_fma_f32 v[120:121], v[0:1], s[4:5], v[120:121] op_sel_hi:[1,0,1]
	v_cvt_f32_f16_e32 v0, v228
	v_pk_fma_f32 v[122:123], v[218:219], s[4:5], v[122:123] op_sel_hi:[1,0,1]
	v_cvt_f32_f16_sdwa v1, v228 dst_sel:DWORD dst_unused:UNUSED_PAD src0_sel:WORD_1
	v_cvt_f32_f16_e32 v218, v229
	v_cvt_f32_f16_sdwa v219, v229 dst_sel:DWORD dst_unused:UNUSED_PAD src0_sel:WORD_1
	v_mov_b32_e32 v149, v3
	v_pk_fma_f32 v[116:117], v[0:1], s[4:5], v[116:117] op_sel_hi:[1,0,1]
	v_cvt_f32_f16_e32 v0, v230
	v_pk_fma_f32 v[118:119], v[218:219], s[4:5], v[118:119] op_sel_hi:[1,0,1]
	v_cvt_f32_f16_sdwa v1, v230 dst_sel:DWORD dst_unused:UNUSED_PAD src0_sel:WORD_1
	v_cvt_f32_f16_e32 v218, v231
	v_cvt_f32_f16_sdwa v219, v231 dst_sel:DWORD dst_unused:UNUSED_PAD src0_sel:WORD_1
	v_mov_b32_e32 v138, v3
	v_pk_fma_f32 v[108:109], v[0:1], s[4:5], v[108:109] op_sel_hi:[1,0,1]
	v_cvt_f32_f16_e32 v0, v232
	v_pk_fma_f32 v[110:111], v[218:219], s[4:5], v[110:111] op_sel_hi:[1,0,1]
	v_cvt_f32_f16_sdwa v1, v232 dst_sel:DWORD dst_unused:UNUSED_PAD src0_sel:WORD_1
	v_cvt_f32_f16_e32 v218, v233
	v_cvt_f32_f16_sdwa v219, v233 dst_sel:DWORD dst_unused:UNUSED_PAD src0_sel:WORD_1
	v_mov_b32_e32 v139, v3
	v_pk_fma_f32 v[92:93], v[0:1], s[4:5], v[92:93] op_sel_hi:[1,0,1]
	v_add_u32_e32 v0, 0x28000, v2
	v_pk_fma_f32 v[94:95], v[218:219], s[4:5], v[94:95] op_sel_hi:[1,0,1]
	v_mov_b32_e32 v1, v3
	v_add_u32_e32 v2, 0x2c000, v2
	v_lshl_add_u64 v[132:133], v[0:1], 1, s[64:65]
	v_lshl_add_u64 v[134:135], v[2:3], 1, s[64:65]
	global_load_dwordx2 v[0:1], v[132:133], off
	global_load_dwordx2 v[146:147], v[132:133], off offset:32
	global_load_dwordx2 v[136:137], v[132:133], off offset:256
	s_nop 0
	global_load_dwordx2 v[132:133], v[132:133], off offset:288
	s_nop 0
	global_load_dwordx2 v[150:151], v[134:135], off
	global_load_dwordx2 v[186:187], v[134:135], off offset:32
	global_load_dwordx2 v[190:191], v[134:135], off offset:256
	global_load_dwordx2 v[194:195], v[134:135], off offset:288
	v_mov_b32_e32 v2, v3
	v_mov_b32_e32 v134, v3
	v_mov_b32_e32 v135, v3
	v_mov_b32_e32 v152, v3
	v_mov_b32_e32 v153, v3
	v_mov_b32_e32 v188, v3
	v_mov_b32_e32 v189, v3
	v_mov_b32_e32 v192, v3
	v_mov_b32_e32 v193, v3
	v_mov_b32_e32 v196, v3
	v_mov_b32_e32 v197, v3
	s_waitcnt vmcnt(7)
	v_mov_b64_e32 v[200:201], v[2:3]
	v_mov_b64_e32 v[198:199], v[0:1]
	s_waitcnt vmcnt(0)
	s_nop 0
	v_cvt_f32_f16_e32 v0, v198
	v_cvt_f32_f16_sdwa v1, v198 dst_sel:DWORD dst_unused:UNUSED_PAD src0_sel:WORD_1
	v_cvt_f32_f16_e32 v134, v199
	v_cvt_f32_f16_sdwa v135, v199 dst_sel:DWORD dst_unused:UNUSED_PAD src0_sel:WORD_1
	v_pk_fma_f32 v[80:81], v[0:1], s[4:5], v[80:81] op_sel_hi:[1,0,1]
	v_cvt_f32_f16_e32 v0, v146
	v_cvt_f32_f16_sdwa v1, v146 dst_sel:DWORD dst_unused:UNUSED_PAD src0_sel:WORD_1
	v_pk_fma_f32 v[82:83], v[134:135], s[4:5], v[82:83] op_sel_hi:[1,0,1]
	v_cvt_f32_f16_e32 v134, v147
	v_cvt_f32_f16_sdwa v135, v147 dst_sel:DWORD dst_unused:UNUSED_PAD src0_sel:WORD_1
	v_pk_fma_f32 v[76:77], v[0:1], s[4:5], v[76:77] op_sel_hi:[1,0,1]
	v_cvt_f32_f16_e32 v0, v136
	v_cvt_f32_f16_sdwa v1, v136 dst_sel:DWORD dst_unused:UNUSED_PAD src0_sel:WORD_1
	v_pk_fma_f32 v[78:79], v[134:135], s[4:5], v[78:79] op_sel_hi:[1,0,1]
	v_cvt_f32_f16_e32 v134, v137
	v_cvt_f32_f16_sdwa v135, v137 dst_sel:DWORD dst_unused:UNUSED_PAD src0_sel:WORD_1
	v_pk_fma_f32 v[64:65], v[0:1], s[4:5], v[64:65] op_sel_hi:[1,0,1]
	v_cvt_f32_f16_e32 v0, v132
	v_cvt_f32_f16_sdwa v1, v132 dst_sel:DWORD dst_unused:UNUSED_PAD src0_sel:WORD_1
	v_cvt_f32_f16_e32 v132, v133
	v_cvt_f32_f16_sdwa v133, v133 dst_sel:DWORD dst_unused:UNUSED_PAD src0_sel:WORD_1
	v_pk_fma_f32 v[66:67], v[134:135], s[4:5], v[66:67] op_sel_hi:[1,0,1]
	v_pk_fma_f32 v[60:61], v[0:1], s[4:5], v[60:61] op_sel_hi:[1,0,1]
	v_cvt_f32_f16_e32 v0, v150
	v_pk_fma_f32 v[62:63], v[132:133], s[4:5], v[62:63] op_sel_hi:[1,0,1]
	v_cvt_f32_f16_sdwa v1, v150 dst_sel:DWORD dst_unused:UNUSED_PAD src0_sel:WORD_1
	v_cvt_f32_f16_e32 v132, v151
	v_cvt_f32_f16_sdwa v133, v151 dst_sel:DWORD dst_unused:UNUSED_PAD src0_sel:WORD_1
	v_mov_b32_e32 v134, v24
	v_pk_fma_f32 v[72:73], v[0:1], s[4:5], v[72:73] op_sel_hi:[1,0,1]
	v_cvt_f32_f16_e32 v0, v186
	v_pk_fma_f32 v[74:75], v[132:133], s[4:5], v[74:75] op_sel_hi:[1,0,1]
	v_cvt_f32_f16_sdwa v1, v186 dst_sel:DWORD dst_unused:UNUSED_PAD src0_sel:WORD_1
	v_cvt_f32_f16_e32 v132, v187
	v_cvt_f32_f16_sdwa v133, v187 dst_sel:DWORD dst_unused:UNUSED_PAD src0_sel:WORD_1
	v_mov_b32_e32 v135, v27
	v_pk_fma_f32 v[68:69], v[0:1], s[4:5], v[68:69] op_sel_hi:[1,0,1]
	v_cvt_f32_f16_e32 v0, v190
	v_pk_fma_f32 v[70:71], v[132:133], s[4:5], v[70:71] op_sel_hi:[1,0,1]
	v_cvt_f32_f16_sdwa v1, v190 dst_sel:DWORD dst_unused:UNUSED_PAD src0_sel:WORD_1
	v_cvt_f32_f16_e32 v132, v191
	v_cvt_f32_f16_sdwa v133, v191 dst_sel:DWORD dst_unused:UNUSED_PAD src0_sel:WORD_1
	v_add_f32_e32 v137, v18, v19
	v_pk_fma_f32 v[56:57], v[0:1], s[4:5], v[56:57] op_sel_hi:[1,0,1]
	v_cvt_f32_f16_e32 v0, v194
	v_pk_fma_f32 v[58:59], v[132:133], s[4:5], v[58:59] op_sel_hi:[1,0,1]
	v_cvt_f32_f16_sdwa v1, v194 dst_sel:DWORD dst_unused:UNUSED_PAD src0_sel:WORD_1
	v_cvt_f32_f16_e32 v132, v195
	v_cvt_f32_f16_sdwa v133, v195 dst_sel:DWORD dst_unused:UNUSED_PAD src0_sel:WORD_1
	v_mov_b32_e32 v136, v9
	v_pk_fma_f32 v[44:45], v[0:1], s[4:5], v[44:45] op_sel_hi:[1,0,1]
	v_mov_b32_e32 v0, v37
	v_pk_fma_f32 v[46:47], v[132:133], s[4:5], v[46:47] op_sel_hi:[1,0,1]
	v_mov_b32_e32 v1, v38
	v_mov_b32_e32 v132, v36
	v_mov_b32_e32 v133, v39
	v_pk_add_f32 v[0:1], v[0:1], v[132:133]
	v_mov_b32_e32 v132, v25
	v_mov_b32_e32 v133, v26
	v_pk_add_f32 v[132:133], v[132:133], v[134:135]
	v_add_f32_e32 v0, v0, v1
	v_pk_add_f32 v[132:133], v[132:133], v[132:133] op_sel_hi:[0,1]
	v_add_f32_e32 v1, 0, v0
	v_add_f32_e32 v135, v16, v17
	v_mov_b32_e32 v134, v8
	v_mov_b32_e32 v132, v10
	v_mov_b32_e32 v0, v11
	v_pk_add_f32 v[134:135], v[134:135], v[136:137]
	v_pk_add_f32 v[0:1], v[132:133], v[0:1]
	s_lshl_b32 s4, s8, 3
	v_pk_add_f32 v[0:1], v[134:135], v[0:1]
	s_add_i32 s7, s4, 0
	v_add_f32_e32 v0, v0, v1
	ds_bpermute_b32 v1, v183, v0
	s_waitcnt lgkmcnt(0)
	v_add_f32_e32 v0, v0, v1
	ds_bpermute_b32 v1, v184, v0
	s_waitcnt lgkmcnt(0)
	v_add_f32_e32 v0, v0, v1
	v_fmamk_f32 v2, v0, 0xbc800000, v39
	v_fmamk_f32 v133, v0, 0xbc800000, v37
	v_fmamk_f32 v1, v0, 0xbc800000, v38
	v_fmamk_f32 v132, v0, 0xbc800000, v36
	v_mul_f32_e32 v133, v133, v133
	v_mul_f32_e32 v2, v2, v2
	v_fmac_f32_e32 v133, v132, v132
	v_fmac_f32_e32 v2, v1, v1
	v_fmamk_f32 v132, v0, 0xbc800000, v27
	v_fmamk_f32 v134, v0, 0xbc800000, v25
	v_add_f32_e32 v1, v133, v2
	v_fmamk_f32 v2, v0, 0xbc800000, v26
	v_fmamk_f32 v133, v0, 0xbc800000, v24
	v_mul_f32_e32 v134, v134, v134
	v_mul_f32_e32 v132, v132, v132
	v_fmac_f32_e32 v134, v133, v133
	v_fmac_f32_e32 v132, v2, v2
	v_add_f32_e32 v2, v134, v132
	v_fmamk_f32 v132, v0, 0xbc800000, v19
	v_fmamk_f32 v134, v0, 0xbc800000, v17
	v_add_f32_e32 v1, v1, v2
	v_fmamk_f32 v2, v0, 0xbc800000, v18
	v_fmamk_f32 v133, v0, 0xbc800000, v16
	v_mul_f32_e32 v134, v134, v134
	v_mul_f32_e32 v132, v132, v132
	v_fmac_f32_e32 v134, v133, v133
	v_fmac_f32_e32 v132, v2, v2
	v_add_f32_e32 v2, v134, v132
	v_fmamk_f32 v132, v0, 0xbc800000, v11
	v_fmamk_f32 v134, v0, 0xbc800000, v9
	v_add_f32_e32 v1, v2, v1
	v_fmamk_f32 v2, v0, 0xbc800000, v10
	v_fmamk_f32 v133, v0, 0xbc800000, v8
	v_mul_f32_e32 v134, v134, v134
	v_mul_f32_e32 v132, v132, v132
	v_fmac_f32_e32 v134, v133, v133
	v_fmac_f32_e32 v132, v2, v2
	v_add_f32_e32 v2, v134, v132
	v_add_f32_e32 v1, v2, v1
	ds_bpermute_b32 v2, v183, v1
	s_waitcnt lgkmcnt(0)
	v_add_f32_e32 v1, v1, v2
	ds_bpermute_b32 v2, v184, v1
	s_and_saveexec_b64 s[4:5], vcc
	s_cbranch_execz .LBB0_1212
	s_lshl_b32 s8, s0, 11
	s_add_i32 s8, s7, s8
	v_mul_f32_e32 v0, 0x3c800000, v0
	s_waitcnt lgkmcnt(0)
	v_add_f32_e32 v1, v1, v2
	v_lshl_add_u32 v2, v144, 5, s8
	ds_write_b64 v2, v[0:1]
